# attention queues: probe one neighbour queue instead of all seven after the own queue runs dry; plus scan loop rewrite, prefetch waitcnt fixes (attention, gdn_prep), P0 norm weight hoist
# speedup vs baseline: 1.2699x; 1.0389x over previous
.LBB0_33:
	s_cmpk_gt_i32 s46, 0x3fff
	s_barrier
	s_cbranch_scc1 .LBB0_44
	v_mov_b32_e32 v33, 0
	v_lshlrev_b32_e32 v32, 4, v218
	v_readlane_b32 s12, v233, 11
	v_lshlrev_b32_e32 v0, 3, v218
	v_mov_b32_e32 v1, v33
	s_add_u32 s4, s48, 0x100000
	v_readlane_b32 s13, v233, 12
	v_readlane_b32 s14, v233, 13
	v_readlane_b32 s15, v233, 14
	v_lshl_add_u64 v[38:39], s[34:35], 0, v[0:1]
	v_add_u32_e32 v0, 0, v32
	s_addc_u32 s5, s49, 0
	v_lshl_add_u64 v[34:35], s[14:15], 0, v[32:33]
	v_lshl_add_u64 v[36:37], s[12:13], 0, v[32:33]
	v_cmp_eq_u32_e32 vcc, 0, v218
	v_cmp_ne_u32_e64 s[6:7], 0, v218
	v_mov_b32_e32 v56, 0x358637bd
	s_mov_b32 s52, 0x800000
	v_add_u32_e32 v57, 0x12000, v0
	v_readlane_b32 s16, v233, 15
	v_readlane_b32 s17, v233, 16
	v_readlane_b32 s18, v233, 17
	v_readlane_b32 s19, v233, 18
	v_readlane_b32 s20, v233, 19
	v_readlane_b32 s21, v233, 20
	v_readlane_b32 s22, v233, 21
	v_readlane_b32 s23, v233, 22
	v_readlane_b32 s24, v233, 23
	v_readlane_b32 s25, v233, 24
	v_readlane_b32 s26, v233, 25
	v_readlane_b32 s27, v233, 26
	global_load_dwordx4 v[76:79], v[34:35], off
	global_load_dwordx4 v[80:83], v[34:35], off offset:1024
	global_load_dwordx4 v[84:87], v[34:35], off offset:2048
	global_load_dwordx4 v[88:91], v[34:35], off offset:3072
	s_branch .LBB0_37
.LBB0_35:
	s_or_b64 exec, exec, s[16:17]
	v_lshlrev_b64 v[20:21], 11, v[40:41]
	v_mul_f32_e32 v12, v12, v32
	v_mul_f32_e32 v13, v13, v32
	v_mul_f32_e32 v14, v14, v32
	v_mul_f32_e32 v15, v15, v32
	v_lshl_add_u64 v[20:21], v[38:39], 0, v[20:21]
	v_mul_f32_e32 v8, v8, v32
	v_mul_f32_e32 v9, v9, v32
	v_mul_f32_e32 v10, v10, v32
	v_mul_f32_e32 v11, v11, v32
	v_mul_f32_e32 v4, v4, v32
	v_mul_f32_e32 v5, v5, v32
	v_mul_f32_e32 v6, v6, v32
	v_mul_f32_e32 v7, v7, v32
	v_mul_f32_e32 v0, v0, v32
	v_mul_f32_e32 v1, v1, v32
	v_mul_f32_e32 v2, v2, v32
	v_mul_f32_e32 v3, v3, v32
	v_mul_f32_e32 v12, v12, v76
	v_mul_f32_e32 v13, v13, v77
	v_mul_f32_e32 v14, v14, v78
	v_mul_f32_e32 v15, v15, v79
	v_cvt_pk_bf16_f32 v12, v12, v13
	v_cvt_pk_bf16_f32 v13, v14, v15
	global_store_dwordx2 v[20:21], v[12:13], off
	v_mul_f32_e32 v8, v8, v80
	v_mul_f32_e32 v9, v9, v81
	v_mul_f32_e32 v10, v10, v82
	v_mul_f32_e32 v11, v11, v83
	v_cvt_pk_bf16_f32 v8, v8, v9
	v_cvt_pk_bf16_f32 v9, v10, v11
	global_store_dwordx2 v[20:21], v[8:9], off offset:512
	v_mul_f32_e32 v4, v4, v84
	v_mul_f32_e32 v5, v5, v85
	v_mul_f32_e32 v6, v6, v86
	v_mul_f32_e32 v7, v7, v87
	v_cvt_pk_bf16_f32 v4, v4, v5
	v_cvt_pk_bf16_f32 v5, v6, v7
	global_store_dwordx2 v[20:21], v[4:5], off offset:1024
	v_mul_f32_e32 v0, v0, v88
	v_mul_f32_e32 v1, v1, v89
	v_mul_f32_e32 v2, v2, v90
	v_mul_f32_e32 v3, v3, v91
	v_cvt_pk_bf16_f32 v0, v0, v1
	v_cvt_pk_bf16_f32 v1, v2, v3
	global_store_dwordx2 v[20:21], v[0:1], off offset:1536

.LBB0_37:
	s_ashr_i32 s47, s46, 31
	s_lshl_b64 s[8:9], s[46:47], 12
	v_lshl_add_u64 v[0:1], v[36:37], 0, s[8:9]
	global_load_dwordx4 v[28:31], v[0:1], off
	global_load_dwordx4 v[24:27], v[0:1], off offset:1024
	global_load_dwordx4 v[20:23], v[0:1], off offset:2048
	global_load_dwordx4 v[16:19], v[0:1], off offset:3072
	ds_read_b128 v[40:43], v57
	ds_read_b128 v[44:47], v57 offset:1024
	ds_read_b128 v[48:51], v57 offset:2048
	ds_read_b128 v[52:55], v57 offset:3072
	ds_read_b128 v[58:61], v57 offset:4096
	ds_read_b128 v[62:65], v57 offset:5120
	s_add_i32 s14, s46, s3
	s_min_i32 s8, s14, 0x3fff
	s_ashr_i32 s9, s8, 31
	s_lshl_b64 s[8:9], s[8:9], 12
	v_lshl_add_u64 v[0:1], v[36:37], 0, s[8:9]
	global_load_dwordx4 v[12:15], v[0:1], off
	global_load_dwordx4 v[8:11], v[0:1], off offset:1024
	global_load_dwordx4 v[4:7], v[0:1], off offset:2048
	s_nop 0
	global_load_dwordx4 v[0:3], v[0:1], off offset:3072
	s_waitcnt vmcnt(7)
	v_mul_f32_e32 v32, v29, v29
	v_mul_f32_e32 v66, v31, v31
	s_waitcnt vmcnt(6)
	v_mul_f32_e32 v67, v25, v25
	v_mul_f32_e32 v68, v27, v27
	s_waitcnt vmcnt(5)
	v_mul_f32_e32 v69, v21, v21
	v_mul_f32_e32 v70, v23, v23
	s_waitcnt lgkmcnt(5)
	v_mul_f32_e32 v41, v29, v41
	v_fmac_f32_e32 v32, v28, v28
	v_fmac_f32_e32 v66, v30, v30
	v_fmac_f32_e32 v67, v24, v24
	v_fmac_f32_e32 v68, v26, v26
	s_waitcnt vmcnt(4)
	v_mul_f32_e32 v71, v17, v17
	v_mul_f32_e32 v72, v19, v19
	v_mul_f32_e32 v43, v31, v43
	v_fmac_f32_e32 v69, v20, v20
	v_fmac_f32_e32 v70, v22, v22
	v_fmac_f32_e32 v41, v28, v40
	v_add_f32_e32 v32, v32, v66
	v_add_f32_e32 v40, v67, v68
	s_waitcnt lgkmcnt(4)
	v_mul_f32_e32 v45, v25, v45
	v_fmac_f32_e32 v71, v16, v16
	v_fmac_f32_e32 v72, v18, v18
	v_fmac_f32_e32 v43, v30, v42
	v_add_f32_e32 v42, v69, v70
	v_add_f32_e32 v32, v32, v40
	v_fmac_f32_e32 v45, v24, v44
	v_add_f32_e32 v44, v71, v72
	v_add_f32_e32 v32, v32, v42
	v_add_f32_e32 v32, v32, v44
	v_mul_f32_e32 v47, v27, v47
	s_waitcnt lgkmcnt(3)
	v_mul_f32_e32 v49, v21, v49
	v_add_f32_dpp v32, v32, v32 quad_perm:[1,0,3,2] row_mask:0xf bank_mask:0xf bound_ctrl:1
	v_mul_f32_e32 v51, v23, v51
	v_fmac_f32_e32 v47, v26, v46
	v_add_f32_dpp v32, v32, v32 quad_perm:[2,3,0,1] row_mask:0xf bank_mask:0xf bound_ctrl:1
	v_add_f32_e32 v41, v41, v43
	s_waitcnt lgkmcnt(2)
	v_mul_f32_e32 v53, v17, v53
	v_add_f32_dpp v32, v32, v32 row_half_mirror row_mask:0xf bank_mask:0xf bound_ctrl:1
	v_mul_f32_e32 v55, v19, v55
	v_fmac_f32_e32 v49, v20, v48
	v_add_f32_dpp v32, v32, v32 row_mirror row_mask:0xf bank_mask:0xf bound_ctrl:1
	v_mov_b32_e32 v42, v32
	s_nop 1
	v_permlane16_swap_b32_e32 v32, v42
	v_add_f32_e32 v32, v32, v42
	v_fmac_f32_e32 v51, v22, v50
	v_add_f32_e32 v43, v45, v47
	v_add_f32_e32 v40, 0, v41
	v_mov_b32_e32 v42, v32
	v_fmac_f32_e32 v53, v16, v52
	v_fmac_f32_e32 v55, v18, v54
	v_add_f32_e32 v45, v49, v51
	v_add_f32_e32 v40, v40, v43
	v_permlane32_swap_b32_e32 v32, v42
	v_add_f32_e32 v46, v53, v55
	v_add_f32_e32 v40, v40, v45
	v_add_f32_e32 v32, v32, v42
	v_add_f32_e32 v40, v40, v46
	v_fmamk_f32 v32, v32, 0x3a800000, v56
	s_waitcnt lgkmcnt(1)
	v_mul_f32_e32 v59, v29, v59
	v_mul_f32_e32 v61, v31, v61
	v_add_f32_dpp v40, v40, v40 quad_perm:[1,0,3,2] row_mask:0xf bank_mask:0xf bound_ctrl:1
	v_mul_f32_e32 v42, 0x4b800000, v32
	v_cmp_gt_f32_e64 s[8:9], s52, v32
	v_fmac_f32_e32 v59, v28, v58
	v_fmac_f32_e32 v61, v30, v60
	v_add_f32_dpp v40, v40, v40 quad_perm:[2,3,0,1] row_mask:0xf bank_mask:0xf bound_ctrl:1
	v_cndmask_b32_e64 v32, v32, v42, s[8:9]
	v_add_f32_e32 v47, v59, v61
	v_add_f32_dpp v40, v40, v40 row_half_mirror row_mask:0xf bank_mask:0xf bound_ctrl:1
	v_rsq_f32_e32 v32, v32
	v_add_f32_e32 v41, 0, v47
	v_add_f32_dpp v40, v40, v40 row_mirror row_mask:0xf bank_mask:0xf bound_ctrl:1
	ds_read_b128 v[44:47], v57 offset:6144
	ds_read_b128 v[48:51], v57 offset:7168
	v_mov_b32_e32 v43, v40
	s_waitcnt lgkmcnt(2)
	v_mul_f32_e32 v63, v25, v63
	v_mul_f32_e32 v65, v27, v65
	v_permlane16_swap_b32_e32 v40, v43
	v_fmac_f32_e32 v63, v24, v62
	v_add_f32_e32 v40, v40, v43
	v_mul_f32_e32 v43, 0x45800000, v32
	v_fmac_f32_e32 v65, v26, v64
	v_cndmask_b32_e64 v32, v32, v43, s[8:9]
	v_add_f32_e32 v43, v63, v65
	v_add_f32_e32 v41, v41, v43
	s_waitcnt lgkmcnt(1)
	v_mul_f32_e32 v43, v21, v45
	v_fmac_f32_e32 v43, v20, v44
	v_mul_f32_e32 v44, v23, v47
	v_fmac_f32_e32 v44, v22, v46
	v_add_f32_e32 v43, v43, v44
	v_add_f32_e32 v41, v41, v43
	s_waitcnt lgkmcnt(0)
	v_mul_f32_e32 v43, v17, v49
	v_mul_f32_e32 v44, v19, v51
	v_fmac_f32_e32 v43, v16, v48
	v_fmac_f32_e32 v44, v18, v50
	v_add_f32_e32 v43, v43, v44
	ds_read_b128 v[44:47], v57 offset:8192
	ds_read_b128 v[48:51], v57 offset:9216
	v_add_f32_e32 v41, v41, v43
	v_mov_b32_e32 v42, v40
	s_nop 1
	v_permlane32_swap_b32_e32 v40, v42
	s_waitcnt lgkmcnt(1)
	v_mul_f32_e32 v45, v29, v45
	v_fmac_f32_e32 v45, v28, v44
	v_mul_f32_e32 v44, v31, v47
	v_fmac_f32_e32 v44, v30, v46
	v_add_f32_e32 v44, v45, v44
	s_waitcnt lgkmcnt(0)
	v_mul_f32_e32 v49, v25, v49
	v_add_f32_e32 v52, 0, v44
	v_fmac_f32_e32 v49, v24, v48
	v_mul_f32_e32 v48, v27, v51
	ds_read_b128 v[44:47], v57 offset:10240
	v_fmac_f32_e32 v48, v26, v50
	v_add_f32_e32 v48, v49, v48
	v_add_f32_e32 v52, v52, v48
	ds_read_b128 v[48:51], v57 offset:11264
	s_waitcnt lgkmcnt(1)
	v_mul_f32_e32 v45, v21, v45
	v_fmac_f32_e32 v45, v20, v44
	v_mul_f32_e32 v44, v23, v47
	v_fmac_f32_e32 v44, v22, v46
	v_add_f32_e32 v44, v45, v44
	s_waitcnt lgkmcnt(0)
	v_mul_f32_e32 v45, v17, v49
	v_mul_f32_e32 v46, v19, v51
	v_fmac_f32_e32 v45, v16, v48
	v_fmac_f32_e32 v46, v18, v50
	v_add_f32_e32 v44, v52, v44
	v_add_f32_e32 v45, v45, v46
	v_add_f32_e32 v44, v44, v45
	ds_read_b128 v[48:51], v57 offset:12288
	ds_read_b128 v[52:55], v57 offset:13312
	v_add_f32_dpp v44, v44, v44 quad_perm:[1,0,3,2] row_mask:0xf bank_mask:0xf bound_ctrl:1
	v_add_f32_dpp v41, v41, v41 quad_perm:[1,0,3,2] row_mask:0xf bank_mask:0xf bound_ctrl:1
	s_waitcnt lgkmcnt(1)
	v_mul_f32_e32 v47, v31, v51
	v_add_f32_dpp v44, v44, v44 quad_perm:[2,3,0,1] row_mask:0xf bank_mask:0xf bound_ctrl:1
	v_fmac_f32_e32 v47, v30, v50
	v_add_f32_dpp v41, v41, v41 quad_perm:[2,3,0,1] row_mask:0xf bank_mask:0xf bound_ctrl:1
	v_add_f32_dpp v44, v44, v44 row_half_mirror row_mask:0xf bank_mask:0xf bound_ctrl:1
	s_nop 0
	v_add_f32_dpp v41, v41, v41 row_half_mirror row_mask:0xf bank_mask:0xf bound_ctrl:1
	v_add_f32_dpp v44, v44, v44 row_mirror row_mask:0xf bank_mask:0xf bound_ctrl:1
	v_mov_b32_e32 v45, v44
	s_nop 1
	v_permlane16_swap_b32_e32 v44, v45
	v_add_f32_e32 v44, v44, v45
	v_mul_f32_e32 v45, v29, v49
	v_fmac_f32_e32 v45, v28, v48
	ds_read_b128 v[48:51], v57 offset:14336
	v_add_f32_e32 v45, v45, v47
	s_waitcnt lgkmcnt(1)
	v_mul_f32_e32 v47, v25, v53
	v_fmac_f32_e32 v47, v24, v52
	v_mul_f32_e32 v52, v27, v55
	v_fmac_f32_e32 v52, v26, v54
	v_add_f32_e32 v45, 0, v45
	v_add_f32_e32 v47, v47, v52
	ds_read_b128 v[52:55], v57 offset:15360
	v_add_f32_e32 v45, v45, v47
	s_waitcnt lgkmcnt(1)
	v_mul_f32_e32 v47, v21, v49
	v_fmac_f32_e32 v47, v20, v48
	v_mul_f32_e32 v48, v23, v51
	v_fmac_f32_e32 v48, v22, v50
	v_add_f32_e32 v47, v47, v48
	v_add_f32_e32 v45, v45, v47
	s_waitcnt lgkmcnt(0)
	v_mul_f32_e32 v47, v17, v53
	v_mul_f32_e32 v48, v19, v55
	v_fmac_f32_e32 v47, v16, v52
	v_fmac_f32_e32 v48, v18, v54
	v_add_f32_e32 v47, v47, v48
	ds_read_b128 v[48:51], v57 offset:16384
	ds_read_b128 v[52:55], v57 offset:17408
	v_add_f32_e32 v45, v45, v47
	v_add_f32_dpp v41, v41, v41 row_mirror row_mask:0xf bank_mask:0xf bound_ctrl:1
	v_mov_b32_e32 v43, v41
	s_waitcnt lgkmcnt(1)
	v_mul_f32_e32 v49, v29, v49
	v_fmac_f32_e32 v49, v28, v48
	v_mul_f32_e32 v48, v31, v51
	v_fmac_f32_e32 v48, v30, v50
	v_add_f32_e32 v48, v49, v48
	s_waitcnt lgkmcnt(0)
	v_mul_f32_e32 v53, v25, v53
	v_add_f32_e32 v58, 0, v48
	v_fmac_f32_e32 v53, v24, v52
	v_mul_f32_e32 v52, v27, v55
	ds_read_b128 v[48:51], v57 offset:18432
	v_fmac_f32_e32 v52, v26, v54
	v_add_f32_e32 v52, v53, v52
	v_add_f32_e32 v58, v58, v52
	ds_read_b128 v[52:55], v57 offset:19456
	s_waitcnt lgkmcnt(1)
	v_mul_f32_e32 v49, v21, v49
	v_fmac_f32_e32 v49, v20, v48
	v_mul_f32_e32 v48, v23, v51
	v_fmac_f32_e32 v48, v22, v50
	v_add_f32_e32 v48, v49, v48
	s_waitcnt lgkmcnt(0)
	v_mul_f32_e32 v49, v17, v53
	v_mul_f32_e32 v50, v19, v55
	v_fmac_f32_e32 v49, v16, v52
	v_fmac_f32_e32 v50, v18, v54
	v_add_f32_e32 v48, v58, v48
	v_add_f32_e32 v49, v49, v50
	v_add_f32_e32 v48, v48, v49
	ds_read_b128 v[52:55], v57 offset:20480
	ds_read_b128 v[58:61], v57 offset:21504
	v_add_f32_dpp v48, v48, v48 quad_perm:[1,0,3,2] row_mask:0xf bank_mask:0xf bound_ctrl:1
	v_add_f32_dpp v45, v45, v45 quad_perm:[1,0,3,2] row_mask:0xf bank_mask:0xf bound_ctrl:1
	v_permlane16_swap_b32_e32 v41, v43
	v_add_f32_dpp v48, v48, v48 quad_perm:[2,3,0,1] row_mask:0xf bank_mask:0xf bound_ctrl:1
	s_waitcnt lgkmcnt(1)
	v_mul_f32_e32 v51, v31, v55
	v_fmac_f32_e32 v51, v30, v54
	v_add_f32_dpp v48, v48, v48 row_half_mirror row_mask:0xf bank_mask:0xf bound_ctrl:1
	v_add_f32_dpp v45, v45, v45 quad_perm:[2,3,0,1] row_mask:0xf bank_mask:0xf bound_ctrl:1
	v_add_f32_e32 v41, v41, v43
	v_add_f32_dpp v48, v48, v48 row_mirror row_mask:0xf bank_mask:0xf bound_ctrl:1
	v_mov_b32_e32 v49, v48
	s_nop 1
	v_permlane16_swap_b32_e32 v48, v49
	v_add_f32_e32 v48, v48, v49
	v_mul_f32_e32 v49, v29, v53
	v_fmac_f32_e32 v49, v28, v52
	ds_read_b128 v[52:55], v57 offset:22528
	v_add_f32_e32 v49, v49, v51
	s_waitcnt lgkmcnt(1)
	v_mul_f32_e32 v51, v25, v59
	v_fmac_f32_e32 v51, v24, v58
	v_mul_f32_e32 v58, v27, v61
	v_fmac_f32_e32 v58, v26, v60
	v_add_f32_e32 v49, 0, v49
	v_add_f32_e32 v51, v51, v58
	ds_read_b128 v[58:61], v57 offset:23552
	v_add_f32_e32 v49, v49, v51
	s_waitcnt lgkmcnt(1)
	v_mul_f32_e32 v51, v21, v53
	v_fmac_f32_e32 v51, v20, v52
	v_mul_f32_e32 v52, v23, v55
	v_fmac_f32_e32 v52, v22, v54
	v_add_f32_e32 v51, v51, v52
	v_add_f32_e32 v49, v49, v51
	s_waitcnt lgkmcnt(0)
	v_mul_f32_e32 v51, v17, v59
	v_mul_f32_e32 v52, v19, v61
	v_fmac_f32_e32 v51, v16, v58
	v_fmac_f32_e32 v52, v18, v60
	v_add_f32_e32 v51, v51, v52
	ds_read_b128 v[52:55], v57 offset:24576
	ds_read_b128 v[58:61], v57 offset:25600
	v_add_f32_e32 v49, v49, v51
	v_add_f32_dpp v45, v45, v45 row_half_mirror row_mask:0xf bank_mask:0xf bound_ctrl:1
	v_mov_b32_e32 v43, v41
	s_waitcnt lgkmcnt(1)
	v_mul_f32_e32 v53, v29, v53
	v_fmac_f32_e32 v53, v28, v52
	v_mul_f32_e32 v52, v31, v55
	v_fmac_f32_e32 v52, v30, v54
	v_add_f32_e32 v52, v53, v52
	s_waitcnt lgkmcnt(0)
	v_mul_f32_e32 v59, v25, v59
	v_add_f32_e32 v62, 0, v52
	v_fmac_f32_e32 v59, v24, v58
	v_mul_f32_e32 v58, v27, v61
	ds_read_b128 v[52:55], v57 offset:26624
	v_fmac_f32_e32 v58, v26, v60
	v_add_f32_e32 v58, v59, v58
	v_add_f32_e32 v62, v62, v58
	ds_read_b128 v[58:61], v57 offset:27648
	s_waitcnt lgkmcnt(1)
	v_mul_f32_e32 v53, v21, v53
	v_fmac_f32_e32 v53, v20, v52
	v_mul_f32_e32 v52, v23, v55
	v_fmac_f32_e32 v52, v22, v54
	v_add_f32_e32 v52, v53, v52
	s_waitcnt lgkmcnt(0)
	v_mul_f32_e32 v53, v17, v59
	v_mul_f32_e32 v54, v19, v61
	v_fmac_f32_e32 v53, v16, v58
	v_fmac_f32_e32 v54, v18, v60
	v_add_f32_e32 v52, v62, v52
	v_add_f32_e32 v53, v53, v54
	v_add_f32_e32 v52, v52, v53
	ds_read_b128 v[58:61], v57 offset:28672
	ds_read_b128 v[62:65], v57 offset:29696
	v_add_f32_dpp v52, v52, v52 quad_perm:[1,0,3,2] row_mask:0xf bank_mask:0xf bound_ctrl:1
	v_add_f32_dpp v49, v49, v49 quad_perm:[1,0,3,2] row_mask:0xf bank_mask:0xf bound_ctrl:1
	v_add_f32_dpp v45, v45, v45 row_mirror row_mask:0xf bank_mask:0xf bound_ctrl:1
	v_add_f32_dpp v52, v52, v52 quad_perm:[2,3,0,1] row_mask:0xf bank_mask:0xf bound_ctrl:1
	s_waitcnt lgkmcnt(1)
	v_mul_f32_e32 v55, v31, v61
	v_fmac_f32_e32 v55, v30, v60
	v_add_f32_dpp v52, v52, v52 row_half_mirror row_mask:0xf bank_mask:0xf bound_ctrl:1
	v_add_f32_dpp v49, v49, v49 quad_perm:[2,3,0,1] row_mask:0xf bank_mask:0xf bound_ctrl:1
	v_mov_b32_e32 v47, v45
	v_add_f32_dpp v52, v52, v52 row_mirror row_mask:0xf bank_mask:0xf bound_ctrl:1
	v_mov_b32_e32 v53, v52
	s_nop 1
	v_permlane16_swap_b32_e32 v52, v53
	v_add_f32_e32 v52, v52, v53
	v_mul_f32_e32 v53, v29, v59
	v_fmac_f32_e32 v53, v28, v58
	ds_read_b128 v[58:61], v57 offset:30720
	v_add_f32_e32 v53, v53, v55
	s_waitcnt lgkmcnt(1)
	v_mul_f32_e32 v55, v25, v63
	v_fmac_f32_e32 v55, v24, v62
	v_mul_f32_e32 v62, v27, v65
	v_fmac_f32_e32 v62, v26, v64
	v_add_f32_e32 v53, 0, v53
	v_add_f32_e32 v55, v55, v62
	ds_read_b128 v[62:65], v57 offset:31744
	v_add_f32_e32 v53, v53, v55
	s_waitcnt lgkmcnt(1)
	v_mul_f32_e32 v55, v21, v59
	v_fmac_f32_e32 v55, v20, v58
	v_mul_f32_e32 v58, v23, v61
	v_fmac_f32_e32 v58, v22, v60
	v_add_f32_e32 v55, v55, v58
	v_add_f32_e32 v53, v53, v55
	s_waitcnt lgkmcnt(0)
	v_mul_f32_e32 v55, v17, v63
	v_mul_f32_e32 v58, v19, v65
	v_fmac_f32_e32 v55, v16, v62
	v_fmac_f32_e32 v58, v18, v64
	v_add_f32_e32 v55, v55, v58
	v_add_f32_e32 v53, v53, v55
	v_add_f32_dpp v49, v49, v49 row_half_mirror row_mask:0xf bank_mask:0xf bound_ctrl:1
	v_permlane16_swap_b32_e32 v45, v47
	v_add_f32_dpp v53, v53, v53 quad_perm:[1,0,3,2] row_mask:0xf bank_mask:0xf bound_ctrl:1
	v_add_f32_dpp v49, v49, v49 row_mirror row_mask:0xf bank_mask:0xf bound_ctrl:1
	v_mov_b32_e32 v51, v49
	v_add_f32_dpp v53, v53, v53 quad_perm:[2,3,0,1] row_mask:0xf bank_mask:0xf bound_ctrl:1
	s_nop 0
	v_permlane16_swap_b32_e32 v49, v51
	v_add_f32_dpp v53, v53, v53 row_half_mirror row_mask:0xf bank_mask:0xf bound_ctrl:1
	v_add_f32_e32 v45, v45, v47
	v_add_f32_e32 v49, v49, v51
	v_add_f32_dpp v53, v53, v53 row_mirror row_mask:0xf bank_mask:0xf bound_ctrl:1
	v_mov_b32_e32 v55, v53
	s_nop 1
	v_permlane16_swap_b32_e32 v53, v55
	v_add_f32_e32 v53, v53, v55
	v_mov_b32_e32 v46, v44
	v_mov_b32_e32 v47, v45
	v_mov_b32_e32 v50, v48
	v_mov_b32_e32 v51, v49
	v_mov_b32_e32 v54, v52
	v_mov_b32_e32 v55, v53
	v_permlane32_swap_b32_e32 v41, v43
	v_permlane32_swap_b32_e32 v44, v46
	v_permlane32_swap_b32_e32 v45, v47
	v_permlane32_swap_b32_e32 v48, v50
	v_permlane32_swap_b32_e32 v49, v51
	v_permlane32_swap_b32_e32 v52, v54
	v_permlane32_swap_b32_e32 v53, v55
	s_waitcnt vmcnt(0)
	s_and_saveexec_b64 s[8:9], vcc
	s_cbranch_execz .LBB0_39
	s_lshl_b64 s[16:17], s[46:47], 5
	v_pk_add_f32 v[40:41], v[40:41], v[42:43]
	v_pk_add_f32 v[42:43], v[44:45], v[46:47]
	s_add_u32 s16, s4, s16
	v_pk_mul_f32 v[42:43], v[32:33], v[42:43] op_sel_hi:[0,1]
	v_pk_mul_f32 v[40:41], v[32:33], v[40:41] op_sel_hi:[0,1]
	v_pk_add_f32 v[44:45], v[48:49], v[50:51]
	v_pk_add_f32 v[46:47], v[52:53], v[54:55]
	s_addc_u32 s17, s5, s17
	v_pk_mul_f32 v[46:47], v[32:33], v[46:47] op_sel_hi:[0,1]
	v_pk_mul_f32 v[44:45], v[32:33], v[44:45] op_sel_hi:[0,1]
	global_store_dwordx4 v33, v[40:43], s[16:17]
	global_store_dwordx4 v33, v[44:47], s[16:17] offset:16
.LBB0_39:
	s_or_b64 exec, exec, s[8:9]
	s_lshl_b64 s[8:9], s[46:47], 11
	v_mul_f32_e32 v28, v28, v32
	v_mul_f32_e32 v29, v29, v32
	v_mul_f32_e32 v30, v30, v32
	v_mul_f32_e32 v31, v31, v32
	v_lshl_add_u64 v[44:45], v[38:39], 0, s[8:9]
	v_mul_f32_e32 v24, v24, v32
	v_mul_f32_e32 v25, v25, v32
	v_mul_f32_e32 v26, v26, v32
	v_mul_f32_e32 v27, v27, v32
	v_mul_f32_e32 v20, v20, v32
	v_mul_f32_e32 v21, v21, v32
	v_mul_f32_e32 v22, v22, v32
	v_mul_f32_e32 v23, v23, v32
	v_mul_f32_e32 v16, v16, v32
	v_mul_f32_e32 v17, v17, v32
	v_mul_f32_e32 v18, v18, v32
	v_mul_f32_e32 v19, v19, v32
	s_cmpk_gt_i32 s14, 0x3fff
	v_mul_f32_e32 v28, v28, v76
	v_mul_f32_e32 v29, v29, v77
	v_mul_f32_e32 v30, v30, v78
	v_mul_f32_e32 v31, v31, v79
	v_cvt_pk_bf16_f32 v28, v28, v29
	v_cvt_pk_bf16_f32 v29, v30, v31
	global_store_dwordx2 v[44:45], v[28:29], off
	v_mul_f32_e32 v24, v24, v80
	v_mul_f32_e32 v25, v25, v81
	v_mul_f32_e32 v26, v26, v82
	v_mul_f32_e32 v27, v27, v83
	v_cvt_pk_bf16_f32 v24, v24, v25
	v_cvt_pk_bf16_f32 v25, v26, v27
	global_store_dwordx2 v[44:45], v[24:25], off offset:512
	v_mul_f32_e32 v20, v20, v84
	v_mul_f32_e32 v21, v21, v85
	v_mul_f32_e32 v22, v22, v86
	v_mul_f32_e32 v23, v23, v87
	v_cvt_pk_bf16_f32 v20, v20, v21
	v_cvt_pk_bf16_f32 v21, v22, v23
	global_store_dwordx2 v[44:45], v[20:21], off offset:1024
	v_mul_f32_e32 v16, v16, v88
	v_mul_f32_e32 v17, v17, v89
	v_mul_f32_e32 v18, v18, v90
	v_mul_f32_e32 v19, v19, v91
	v_cvt_pk_bf16_f32 v16, v16, v17
	v_cvt_pk_bf16_f32 v17, v18, v19
	global_store_dwordx2 v[44:45], v[16:17], off offset:1536
	s_cbranch_scc1 .LBB0_36
	v_mul_f32_e32 v16, v13, v13
	v_mul_f32_e32 v17, v15, v15
	v_fmac_f32_e32 v16, v12, v12
	v_fmac_f32_e32 v17, v14, v14
	v_add_f32_e32 v16, v16, v17
	v_mul_f32_e32 v17, v9, v9
	v_mul_f32_e32 v18, v11, v11
	v_fmac_f32_e32 v17, v8, v8
	v_fmac_f32_e32 v18, v10, v10
	v_add_f32_e32 v17, v17, v18
	v_add_f32_e32 v16, v16, v17
	v_mul_f32_e32 v17, v5, v5
	v_mul_f32_e32 v18, v7, v7
	v_fmac_f32_e32 v17, v4, v4
	v_fmac_f32_e32 v18, v6, v6
	v_add_f32_e32 v17, v17, v18
	v_add_f32_e32 v16, v16, v17
	v_mul_f32_e32 v17, v1, v1
	v_mul_f32_e32 v18, v3, v3
	v_fmac_f32_e32 v17, v0, v0
	v_fmac_f32_e32 v18, v2, v2
	v_add_f32_e32 v17, v17, v18
	v_add_f32_e32 v16, v16, v17
	s_nop 1
	v_add_f32_dpp v16, v16, v16 quad_perm:[1,0,3,2] row_mask:0xf bank_mask:0xf bound_ctrl:1
	s_nop 1
	v_add_f32_dpp v16, v16, v16 quad_perm:[2,3,0,1] row_mask:0xf bank_mask:0xf bound_ctrl:1
	s_nop 1
	v_add_f32_dpp v16, v16, v16 row_half_mirror row_mask:0xf bank_mask:0xf bound_ctrl:1
	s_nop 1
	v_add_f32_dpp v16, v16, v16 row_mirror row_mask:0xf bank_mask:0xf bound_ctrl:1
	v_mov_b32_e32 v17, v16
	s_nop 1
	v_permlane16_swap_b32_e32 v16, v17
	v_add_f32_e32 v20, v16, v17
	v_mov_b32_e32 v21, v20
	ds_read_b128 v[16:19], v57
	s_nop 0
	v_permlane32_swap_b32_e32 v20, v21
	v_add_f32_e32 v20, v20, v21
	v_fmamk_f32 v32, v20, 0x3a800000, v56
	ds_read_b128 v[20:23], v57 offset:1024
	s_waitcnt lgkmcnt(1)
	v_mul_f32_e32 v17, v13, v17
	v_fmac_f32_e32 v17, v12, v16
	v_mul_f32_e32 v16, v15, v19
	v_fmac_f32_e32 v16, v14, v18
	v_add_f32_e32 v16, v17, v16
	s_waitcnt lgkmcnt(0)
	v_mul_f32_e32 v21, v9, v21
	v_add_f32_e32 v24, 0, v16
	v_fmac_f32_e32 v21, v8, v20
	v_mul_f32_e32 v20, v11, v23
	ds_read_b128 v[16:19], v57 offset:2048
	v_fmac_f32_e32 v20, v10, v22
	v_add_f32_e32 v20, v21, v20
	v_add_f32_e32 v24, v24, v20
	ds_read_b128 v[20:23], v57 offset:3072
	s_waitcnt lgkmcnt(1)
	v_mul_f32_e32 v17, v5, v17
	v_fmac_f32_e32 v17, v4, v16
	v_mul_f32_e32 v16, v7, v19
	v_fmac_f32_e32 v16, v6, v18
	v_add_f32_e32 v16, v17, v16
	s_waitcnt lgkmcnt(0)
	v_mul_f32_e32 v17, v1, v21
	v_mul_f32_e32 v18, v3, v23
	v_fmac_f32_e32 v17, v0, v20
	v_fmac_f32_e32 v18, v2, v22
	v_add_f32_e32 v16, v24, v16
	v_add_f32_e32 v17, v17, v18
	v_add_f32_e32 v16, v16, v17
	ds_read_b128 v[20:23], v57 offset:4096
	ds_read_b128 v[24:27], v57 offset:5120
	v_add_f32_dpp v16, v16, v16 quad_perm:[1,0,3,2] row_mask:0xf bank_mask:0xf bound_ctrl:1
	v_cmp_gt_f32_e64 s[8:9], s52, v32
	s_waitcnt lgkmcnt(1)
	v_mul_f32_e32 v19, v15, v23
	v_add_f32_dpp v16, v16, v16 quad_perm:[2,3,0,1] row_mask:0xf bank_mask:0xf bound_ctrl:1
	v_fmac_f32_e32 v19, v14, v22
	s_nop 0
	v_add_f32_dpp v16, v16, v16 row_half_mirror row_mask:0xf bank_mask:0xf bound_ctrl:1
	s_nop 1
	v_add_f32_dpp v16, v16, v16 row_mirror row_mask:0xf bank_mask:0xf bound_ctrl:1
	v_mov_b32_e32 v17, v16
	s_nop 1
	v_permlane16_swap_b32_e32 v16, v17
	v_add_f32_e32 v16, v16, v17
	v_mul_f32_e32 v17, v13, v21
	v_fmac_f32_e32 v17, v12, v20
	ds_read_b128 v[20:23], v57 offset:6144
	v_add_f32_e32 v17, v17, v19
	s_waitcnt lgkmcnt(1)
	v_mul_f32_e32 v19, v9, v25
	v_fmac_f32_e32 v19, v8, v24
	v_mul_f32_e32 v24, v11, v27
	v_fmac_f32_e32 v24, v10, v26
	v_add_f32_e32 v17, 0, v17
	v_add_f32_e32 v19, v19, v24
	ds_read_b128 v[24:27], v57 offset:7168
	v_add_f32_e32 v17, v17, v19
	s_waitcnt lgkmcnt(1)
	v_mul_f32_e32 v19, v5, v21
	v_fmac_f32_e32 v19, v4, v20
	v_mul_f32_e32 v20, v7, v23
	v_fmac_f32_e32 v20, v6, v22
	v_add_f32_e32 v19, v19, v20
	v_add_f32_e32 v17, v17, v19
	s_waitcnt lgkmcnt(0)
	v_mul_f32_e32 v19, v1, v25
	v_mul_f32_e32 v20, v3, v27
	v_fmac_f32_e32 v19, v0, v24
	v_fmac_f32_e32 v20, v2, v26
	v_add_f32_e32 v19, v19, v20
	ds_read_b128 v[20:23], v57 offset:8192
	ds_read_b128 v[24:27], v57 offset:9216
	v_add_f32_e32 v17, v17, v19
	v_mov_b32_e32 v18, v16
	s_nop 1
	v_permlane32_swap_b32_e32 v16, v18
	s_waitcnt lgkmcnt(1)
	v_mul_f32_e32 v21, v13, v21
	v_fmac_f32_e32 v21, v12, v20
	v_mul_f32_e32 v20, v15, v23
	v_fmac_f32_e32 v20, v14, v22
	v_add_f32_e32 v20, v21, v20
	s_waitcnt lgkmcnt(0)
	v_mul_f32_e32 v25, v9, v25
	v_add_f32_e32 v28, 0, v20
	v_fmac_f32_e32 v25, v8, v24
	v_mul_f32_e32 v24, v11, v27
	ds_read_b128 v[20:23], v57 offset:10240
	v_fmac_f32_e32 v24, v10, v26
	v_add_f32_e32 v24, v25, v24
	v_add_f32_e32 v28, v28, v24
	ds_read_b128 v[24:27], v57 offset:11264
	s_waitcnt lgkmcnt(1)
	v_mul_f32_e32 v21, v5, v21
	v_fmac_f32_e32 v21, v4, v20
	v_mul_f32_e32 v20, v7, v23
	v_fmac_f32_e32 v20, v6, v22
	v_add_f32_e32 v20, v21, v20
	s_waitcnt lgkmcnt(0)
	v_mul_f32_e32 v21, v1, v25
	v_mul_f32_e32 v22, v3, v27
	v_fmac_f32_e32 v21, v0, v24
	v_fmac_f32_e32 v22, v2, v26
	v_add_f32_e32 v20, v28, v20
	v_add_f32_e32 v21, v21, v22
	v_add_f32_e32 v20, v20, v21
	ds_read_b128 v[24:27], v57 offset:12288
	ds_read_b128 v[28:31], v57 offset:13312
	v_add_f32_dpp v20, v20, v20 quad_perm:[1,0,3,2] row_mask:0xf bank_mask:0xf bound_ctrl:1
	v_add_f32_dpp v17, v17, v17 quad_perm:[1,0,3,2] row_mask:0xf bank_mask:0xf bound_ctrl:1
	s_waitcnt lgkmcnt(1)
	v_mul_f32_e32 v23, v15, v27
	v_add_f32_dpp v20, v20, v20 quad_perm:[2,3,0,1] row_mask:0xf bank_mask:0xf bound_ctrl:1
	v_fmac_f32_e32 v23, v14, v26
	v_add_f32_dpp v17, v17, v17 quad_perm:[2,3,0,1] row_mask:0xf bank_mask:0xf bound_ctrl:1
	v_add_f32_dpp v20, v20, v20 row_half_mirror row_mask:0xf bank_mask:0xf bound_ctrl:1
	s_nop 0
	v_add_f32_dpp v17, v17, v17 row_half_mirror row_mask:0xf bank_mask:0xf bound_ctrl:1
	v_add_f32_dpp v20, v20, v20 row_mirror row_mask:0xf bank_mask:0xf bound_ctrl:1
	v_mov_b32_e32 v21, v20
	s_nop 1
	v_permlane16_swap_b32_e32 v20, v21
	v_add_f32_e32 v20, v20, v21
	v_mul_f32_e32 v21, v13, v25
	v_fmac_f32_e32 v21, v12, v24
	ds_read_b128 v[24:27], v57 offset:14336
	v_add_f32_e32 v21, v21, v23
	s_waitcnt lgkmcnt(1)
	v_mul_f32_e32 v23, v9, v29
	v_fmac_f32_e32 v23, v8, v28
	v_mul_f32_e32 v28, v11, v31
	v_fmac_f32_e32 v28, v10, v30
	v_add_f32_e32 v21, 0, v21
	v_add_f32_e32 v23, v23, v28
	ds_read_b128 v[28:31], v57 offset:15360
	v_add_f32_e32 v21, v21, v23
	s_waitcnt lgkmcnt(1)
	v_mul_f32_e32 v23, v5, v25
	v_fmac_f32_e32 v23, v4, v24
	v_mul_f32_e32 v24, v7, v27
	v_fmac_f32_e32 v24, v6, v26
	v_add_f32_e32 v23, v23, v24
	v_add_f32_e32 v21, v21, v23
	s_waitcnt lgkmcnt(0)
	v_mul_f32_e32 v23, v1, v29
	v_mul_f32_e32 v24, v3, v31
	v_fmac_f32_e32 v23, v0, v28
	v_fmac_f32_e32 v24, v2, v30
	v_add_f32_e32 v23, v23, v24
	ds_read_b128 v[24:27], v57 offset:16384
	ds_read_b128 v[28:31], v57 offset:17408
	v_add_f32_e32 v21, v21, v23
	v_add_f32_dpp v17, v17, v17 row_mirror row_mask:0xf bank_mask:0xf bound_ctrl:1
	v_mov_b32_e32 v19, v17
	s_waitcnt lgkmcnt(1)
	v_mul_f32_e32 v25, v13, v25
	v_fmac_f32_e32 v25, v12, v24
	v_mul_f32_e32 v24, v15, v27
	v_fmac_f32_e32 v24, v14, v26
	v_add_f32_e32 v24, v25, v24
	s_waitcnt lgkmcnt(0)
	v_mul_f32_e32 v29, v9, v29
	v_add_f32_e32 v40, 0, v24
	v_fmac_f32_e32 v29, v8, v28
	v_mul_f32_e32 v28, v11, v31
	ds_read_b128 v[24:27], v57 offset:18432
	v_fmac_f32_e32 v28, v10, v30
	v_add_f32_e32 v28, v29, v28
	v_add_f32_e32 v40, v40, v28
	ds_read_b128 v[28:31], v57 offset:19456
	s_waitcnt lgkmcnt(1)
	v_mul_f32_e32 v25, v5, v25
	v_fmac_f32_e32 v25, v4, v24
	v_mul_f32_e32 v24, v7, v27
	v_fmac_f32_e32 v24, v6, v26
	v_add_f32_e32 v24, v25, v24
	s_waitcnt lgkmcnt(0)
	v_mul_f32_e32 v25, v1, v29
	v_mul_f32_e32 v26, v3, v31
	v_fmac_f32_e32 v25, v0, v28
	v_fmac_f32_e32 v26, v2, v30
	v_add_f32_e32 v24, v40, v24
	v_add_f32_e32 v25, v25, v26
	v_add_f32_e32 v24, v24, v25
	ds_read_b128 v[28:31], v57 offset:20480
	ds_read_b128 v[40:43], v57 offset:21504
	v_add_f32_dpp v24, v24, v24 quad_perm:[1,0,3,2] row_mask:0xf bank_mask:0xf bound_ctrl:1
	v_add_f32_dpp v21, v21, v21 quad_perm:[1,0,3,2] row_mask:0xf bank_mask:0xf bound_ctrl:1
	v_permlane16_swap_b32_e32 v17, v19
	v_add_f32_dpp v24, v24, v24 quad_perm:[2,3,0,1] row_mask:0xf bank_mask:0xf bound_ctrl:1
	s_waitcnt lgkmcnt(1)
	v_mul_f32_e32 v27, v15, v31
	v_fmac_f32_e32 v27, v14, v30
	v_add_f32_dpp v24, v24, v24 row_half_mirror row_mask:0xf bank_mask:0xf bound_ctrl:1
	v_add_f32_dpp v21, v21, v21 quad_perm:[2,3,0,1] row_mask:0xf bank_mask:0xf bound_ctrl:1
	v_add_f32_e32 v17, v17, v19
	v_add_f32_dpp v24, v24, v24 row_mirror row_mask:0xf bank_mask:0xf bound_ctrl:1
	v_mov_b32_e32 v25, v24
	s_nop 1
	v_permlane16_swap_b32_e32 v24, v25
	v_add_f32_e32 v24, v24, v25
	v_mul_f32_e32 v25, v13, v29
	v_fmac_f32_e32 v25, v12, v28
	ds_read_b128 v[28:31], v57 offset:22528
	v_add_f32_e32 v25, v25, v27
	s_waitcnt lgkmcnt(1)
	v_mul_f32_e32 v27, v9, v41
	v_fmac_f32_e32 v27, v8, v40
	v_mul_f32_e32 v40, v11, v43
	v_fmac_f32_e32 v40, v10, v42
	v_add_f32_e32 v25, 0, v25
	v_add_f32_e32 v27, v27, v40
	ds_read_b128 v[40:43], v57 offset:23552
	v_add_f32_e32 v25, v25, v27
	s_waitcnt lgkmcnt(1)
	v_mul_f32_e32 v27, v5, v29
	v_fmac_f32_e32 v27, v4, v28
	v_mul_f32_e32 v28, v7, v31
	v_fmac_f32_e32 v28, v6, v30
	v_add_f32_e32 v27, v27, v28
	v_add_f32_e32 v25, v25, v27
	s_waitcnt lgkmcnt(0)
	v_mul_f32_e32 v27, v1, v41
	v_mul_f32_e32 v28, v3, v43
	v_fmac_f32_e32 v27, v0, v40
	v_fmac_f32_e32 v28, v2, v42
	v_add_f32_e32 v27, v27, v28
	ds_read_b128 v[28:31], v57 offset:24576
	ds_read_b128 v[40:43], v57 offset:25600
	v_add_f32_e32 v25, v25, v27
	v_add_f32_dpp v21, v21, v21 row_half_mirror row_mask:0xf bank_mask:0xf bound_ctrl:1
	v_mov_b32_e32 v19, v17
	s_waitcnt lgkmcnt(1)
	v_mul_f32_e32 v29, v13, v29
	v_fmac_f32_e32 v29, v12, v28
	v_mul_f32_e32 v28, v15, v31
	v_fmac_f32_e32 v28, v14, v30
	v_add_f32_e32 v28, v29, v28
	s_waitcnt lgkmcnt(0)
	v_mul_f32_e32 v41, v9, v41
	v_add_f32_e32 v44, 0, v28
	v_fmac_f32_e32 v41, v8, v40
	v_mul_f32_e32 v40, v11, v43
	ds_read_b128 v[28:31], v57 offset:26624
	v_fmac_f32_e32 v40, v10, v42
	v_add_f32_e32 v40, v41, v40
	v_add_f32_e32 v44, v44, v40
	ds_read_b128 v[40:43], v57 offset:27648
	s_waitcnt lgkmcnt(1)
	v_mul_f32_e32 v29, v5, v29
	v_fmac_f32_e32 v29, v4, v28
	v_mul_f32_e32 v28, v7, v31
	v_fmac_f32_e32 v28, v6, v30
	v_add_f32_e32 v28, v29, v28
	s_waitcnt lgkmcnt(0)
	v_mul_f32_e32 v29, v1, v41
	v_mul_f32_e32 v30, v3, v43
	v_fmac_f32_e32 v29, v0, v40
	v_fmac_f32_e32 v30, v2, v42
	v_add_f32_e32 v28, v44, v28
	v_add_f32_e32 v29, v29, v30
	v_add_f32_e32 v28, v28, v29
	ds_read_b128 v[40:43], v57 offset:28672
	ds_read_b128 v[44:47], v57 offset:29696
	v_add_f32_dpp v28, v28, v28 quad_perm:[1,0,3,2] row_mask:0xf bank_mask:0xf bound_ctrl:1
	v_add_f32_dpp v25, v25, v25 quad_perm:[1,0,3,2] row_mask:0xf bank_mask:0xf bound_ctrl:1
	v_add_f32_dpp v21, v21, v21 row_mirror row_mask:0xf bank_mask:0xf bound_ctrl:1
	v_add_f32_dpp v28, v28, v28 quad_perm:[2,3,0,1] row_mask:0xf bank_mask:0xf bound_ctrl:1
	s_waitcnt lgkmcnt(1)
	v_mul_f32_e32 v31, v15, v43
	v_fmac_f32_e32 v31, v14, v42
	v_add_f32_dpp v28, v28, v28 row_half_mirror row_mask:0xf bank_mask:0xf bound_ctrl:1
	v_add_f32_dpp v25, v25, v25 quad_perm:[2,3,0,1] row_mask:0xf bank_mask:0xf bound_ctrl:1
	v_mov_b32_e32 v23, v21
	v_add_f32_dpp v28, v28, v28 row_mirror row_mask:0xf bank_mask:0xf bound_ctrl:1
	v_mov_b32_e32 v29, v28
	s_nop 1
	v_permlane16_swap_b32_e32 v28, v29
	v_add_f32_e32 v28, v28, v29
	v_mul_f32_e32 v29, v13, v41
	v_fmac_f32_e32 v29, v12, v40
	ds_read_b128 v[40:43], v57 offset:30720
	v_add_f32_e32 v29, v29, v31
	s_waitcnt lgkmcnt(1)
	v_mul_f32_e32 v31, v9, v45
	v_fmac_f32_e32 v31, v8, v44
	v_mul_f32_e32 v44, v11, v47
	v_fmac_f32_e32 v44, v10, v46
	v_add_f32_e32 v29, 0, v29
	v_add_f32_e32 v31, v31, v44
	ds_read_b128 v[44:47], v57 offset:31744
	v_add_f32_e32 v29, v29, v31
	s_waitcnt lgkmcnt(1)
	v_mul_f32_e32 v31, v5, v41
	v_fmac_f32_e32 v31, v4, v40
	v_mul_f32_e32 v40, v7, v43
	v_fmac_f32_e32 v40, v6, v42
	v_add_f32_e32 v31, v31, v40
	v_add_f32_e32 v29, v29, v31
	s_waitcnt lgkmcnt(0)
	v_mul_f32_e32 v31, v1, v45
	v_mul_f32_e32 v40, v3, v47
	v_fmac_f32_e32 v31, v0, v44
	v_fmac_f32_e32 v40, v2, v46
	v_add_f32_e32 v31, v31, v40
	v_add_f32_e32 v29, v29, v31
	v_add_f32_dpp v25, v25, v25 row_half_mirror row_mask:0xf bank_mask:0xf bound_ctrl:1
	v_permlane16_swap_b32_e32 v21, v23
	v_add_f32_dpp v29, v29, v29 quad_perm:[1,0,3,2] row_mask:0xf bank_mask:0xf bound_ctrl:1
	v_add_f32_dpp v25, v25, v25 row_mirror row_mask:0xf bank_mask:0xf bound_ctrl:1
	v_mov_b32_e32 v27, v25
	v_add_f32_dpp v29, v29, v29 quad_perm:[2,3,0,1] row_mask:0xf bank_mask:0xf bound_ctrl:1
	s_nop 0
	v_permlane16_swap_b32_e32 v25, v27
	v_add_f32_dpp v29, v29, v29 row_half_mirror row_mask:0xf bank_mask:0xf bound_ctrl:1
	v_add_f32_e32 v21, v21, v23
	v_add_f32_e32 v25, v25, v27
	v_add_f32_dpp v29, v29, v29 row_mirror row_mask:0xf bank_mask:0xf bound_ctrl:1
	v_mov_b32_e32 v31, v29
	s_nop 1
	v_permlane16_swap_b32_e32 v29, v31
	v_add_f32_e32 v29, v29, v31
	v_mov_b32_e32 v22, v20
	v_mov_b32_e32 v23, v21
	v_mov_b32_e32 v26, v24
	v_mov_b32_e32 v27, v25
	v_mov_b32_e32 v30, v28
	v_mov_b32_e32 v31, v29
	v_permlane32_swap_b32_e32 v17, v19
	v_permlane32_swap_b32_e32 v20, v22
	v_permlane32_swap_b32_e32 v21, v23
	v_permlane32_swap_b32_e32 v24, v26
	v_permlane32_swap_b32_e32 v25, v27
	v_permlane32_swap_b32_e32 v28, v30
	v_permlane32_swap_b32_e32 v29, v31
	s_and_saveexec_b64 s[16:17], s[6:7]
	s_xor_b64 s[16:17], exec, s[16:17]
	s_ashr_i32 s15, s14, 31
	s_or_saveexec_b64 s[16:17], s[16:17]
	v_mul_f32_e32 v40, 0x4b800000, v32
	v_cndmask_b32_e64 v32, v32, v40, s[8:9]
	v_rsq_f32_e32 v32, v32
	s_nop 0
	v_mul_f32_e32 v40, 0x45800000, v32
	v_cndmask_b32_e64 v32, v32, v40, s[8:9]
	v_mov_b64_e32 v[40:41], s[14:15]
	s_xor_b64 exec, exec, s[16:17]
	s_cbranch_execz .LBB0_35
	s_ashr_i32 s15, s14, 31
	s_lshl_b64 s[8:9], s[14:15], 5
	v_pk_add_f32 v[16:17], v[16:17], v[18:19]
	v_pk_add_f32 v[18:19], v[20:21], v[22:23]
	s_add_u32 s8, s4, s8
	v_pk_mul_f32 v[18:19], v[32:33], v[18:19] op_sel_hi:[0,1]
	v_pk_mul_f32 v[16:17], v[32:33], v[16:17] op_sel_hi:[0,1]
	v_pk_add_f32 v[20:21], v[24:25], v[26:27]
	v_pk_add_f32 v[22:23], v[28:29], v[30:31]
	s_addc_u32 s9, s5, s9
	v_mov_b64_e32 v[40:41], s[14:15]
	v_pk_mul_f32 v[22:23], v[32:33], v[22:23] op_sel_hi:[0,1]
	v_pk_mul_f32 v[20:21], v[32:33], v[20:21] op_sel_hi:[0,1]
	global_store_dwordx4 v33, v[16:19], s[8:9]
	global_store_dwordx4 v33, v[20:23], s[8:9] offset:16
	s_branch .LBB0_35

.LBB0_240:
	v_cmp_ne_u32_e32 vcc, s58, v131
	s_and_saveexec_b64 s[6:7], vcc
	s_cbranch_execz .LBB0_242
	s_lshl_b32 s8, s58, 7
	v_or3_b32 v0, v132, s8, v134
	v_readlane_b32 s8, v233, 11
	v_ashrrev_i32_e32 v1, 31, v0
	v_readlane_b32 s14, v233, 17
	v_readlane_b32 s15, v233, 18
	v_readlane_b32 s9, v233, 12
	s_mov_b64 s[8:9], 0x1800
	v_lshl_add_u64 v[24:25], v[0:1], 2, s[14:15]
	v_add_co_u32_e32 v10, vcc, 0x1000, v24
	v_lshl_add_u64 v[8:9], v[24:25], 0, s[8:9]
	s_nop 0
	v_addc_co_u32_e32 v11, vcc, 0, v25, vcc
	s_mov_b64 s[8:9], 0x3000
	v_add_co_u32_e32 v18, vcc, 0x3000, v24
	v_lshl_add_u64 v[16:17], v[24:25], 0, s[8:9]
	s_nop 0
	v_addc_co_u32_e32 v19, vcc, 0, v25, vcc
	s_mov_b64 s[8:9], 0x4800
	global_load_dwordx4 v[0:3], v[24:25], off offset:16
	global_load_dwordx4 v[4:7], v[24:25], off
	v_lshl_add_u64 v[26:27], v[24:25], 0, s[8:9]
	v_add_co_u32_e32 v24, vcc, 0x4000, v24
	global_load_dwordx4 v[12:15], v[10:11], off offset:2048
	s_nop 0
	global_load_dwordx4 v[8:11], v[8:9], off offset:16
	v_addc_co_u32_e32 v25, vcc, 0, v25, vcc
	global_load_dwordx4 v[20:23], v[18:19], off
	s_nop 0
	global_load_dwordx4 v[16:19], v[16:17], off offset:16
	s_nop 0
	global_load_dwordx4 v[28:31], v[24:25], off offset:2048
	s_nop 0
	global_load_dwordx4 v[24:27], v[26:27], off offset:16
	v_mov_b32_e32 v131, s58
	v_readlane_b32 s10, v233, 13
	v_readlane_b32 s11, v233, 14
	v_readlane_b32 s12, v233, 15
	v_readlane_b32 s13, v233, 16
	v_readlane_b32 s16, v233, 19
	v_readlane_b32 s17, v233, 20
	v_readlane_b32 s18, v233, 21
	v_readlane_b32 s19, v233, 22
	v_readlane_b32 s20, v233, 23
	v_readlane_b32 s21, v233, 24
	v_readlane_b32 s22, v233, 25
	v_readlane_b32 s23, v233, 26
	s_waitcnt vmcnt(0)
.LBB0_242:
	s_or_b64 exec, exec, s[6:7]
	v_lshlrev_b32_e32 v38, 16, v64
	v_and_b32_e32 v39, 0xffff0000, v64
	v_lshlrev_b32_e32 v140, 16, v68
	v_and_b32_e32 v141, 0xffff0000, v68
	v_pk_fma_f32 v[38:39], v[4:5], v[38:39], 0 op_sel_hi:[1,1,0]
	v_lshlrev_b32_e32 v138, 16, v76
	v_and_b32_e32 v139, 0xffff0000, v76
	v_pk_fma_f32 v[38:39], v[12:13], v[140:141], v[38:39]
	v_lshlrev_b32_e32 v37, 1, v134
	v_lshlrev_b32_e32 v129, 2, v134
	v_lshlrev_b32_e32 v134, 16, v72
	v_and_b32_e32 v135, 0xffff0000, v72
	v_pk_fma_f32 v[38:39], v[20:21], v[138:139], v[38:39]
	v_lshlrev_b32_e32 v154, 16, v69
	v_and_b32_e32 v155, 0xffff0000, v69
	v_pk_fma_f32 v[68:69], v[28:29], v[134:135], v[38:39]
	v_lshlrev_b32_e32 v152, 16, v70
	v_mul_f32_e32 v38, 0xbfb8aa3b, v68
	v_exp_f32_e32 v38, v38
	v_mul_f32_e32 v39, 0xbfb8aa3b, v69
	v_exp_f32_e32 v39, v39
	v_and_b32_e32 v153, 0xffff0000, v70
	v_add_f32_e32 v38, 1.0, v38
	v_rcp_f32_e32 v70, v38
	v_add_f32_e32 v38, 1.0, v39
	v_lshlrev_b32_e32 v64, 16, v65
	v_and_b32_e32 v65, 0xffff0000, v65
	v_lshlrev_b32_e32 v144, 16, v71
	v_and_b32_e32 v145, 0xffff0000, v71
	v_rcp_f32_e32 v71, v38
	v_pk_fma_f32 v[64:65], v[6:7], v[64:65], 0 op_sel_hi:[1,1,0]
	v_lshlrev_b32_e32 v150, 16, v77
	v_and_b32_e32 v151, 0xffff0000, v77
	v_pk_fma_f32 v[64:65], v[14:15], v[154:155], v[64:65]
	v_lshlrev_b32_e32 v76, 16, v73
	v_and_b32_e32 v77, 0xffff0000, v73
	v_pk_fma_f32 v[64:65], v[22:23], v[150:151], v[64:65]
	v_lshlrev_b32_e32 v148, 16, v78
	v_pk_fma_f32 v[64:65], v[30:31], v[76:77], v[64:65]
	v_and_b32_e32 v149, 0xffff0000, v78
	v_lshlrev_b32_e32 v142, 16, v79
	v_and_b32_e32 v143, 0xffff0000, v79
	v_lshlrev_b32_e32 v78, 16, v74
	v_and_b32_e32 v79, 0xffff0000, v74
	v_lshlrev_b32_e32 v38, 16, v75
	v_and_b32_e32 v39, 0xffff0000, v75
	v_pk_mul_f32 v[68:69], v[68:69], v[70:71]
	v_mul_f32_e32 v70, 0xbfb8aa3b, v64
	v_mul_f32_e32 v71, 0xbfb8aa3b, v65
	v_lshlrev_b32_e32 v74, 16, v66
	v_and_b32_e32 v75, 0xffff0000, v66
	v_exp_f32_e32 v70, v70
	v_exp_f32_e32 v71, v71
	v_pk_fma_f32 v[74:75], v[0:1], v[74:75], 0 op_sel_hi:[1,1,0]
	v_cmp_lt_u32_e32 vcc, 15, v127
	v_pk_fma_f32 v[74:75], v[8:9], v[152:153], v[74:75]
	v_add_f32_e32 v70, 1.0, v70
	v_pk_fma_f32 v[74:75], v[16:17], v[148:149], v[74:75]
	v_add_f32_e32 v71, 1.0, v71
	v_pk_fma_f32 v[74:75], v[24:25], v[78:79], v[74:75]
	v_rcp_f32_e32 v70, v70
	v_mul_f32_e32 v66, 0xbfb8aa3b, v74
	v_rcp_f32_e32 v71, v71
	v_exp_f32_e32 v66, v66
	v_cmp_gt_u32_e64 s[8:9], 16, v127
	v_mul_f32_e32 v127, 0xbfb8aa3b, v75
	v_pk_mul_f32 v[70:71], v[64:65], v[70:71]
	v_add_f32_e32 v64, 1.0, v66
	v_lshlrev_b32_e32 v66, 16, v67
	v_and_b32_e32 v67, 0xffff0000, v67
	v_exp_f32_e32 v127, v127
	v_pk_fma_f32 v[66:67], v[2:3], v[66:67], 0 op_sel_hi:[1,1,0]
	v_rcp_f32_e32 v64, v64
	v_pk_fma_f32 v[66:67], v[10:11], v[144:145], v[66:67]
	v_add_f32_e32 v65, 1.0, v127
	v_pk_fma_f32 v[66:67], v[18:19], v[142:143], v[66:67]
	v_rcp_f32_e32 v65, v65
	v_pk_fma_f32 v[66:67], v[26:27], v[38:39], v[66:67]
	v_pk_mul_f32 v[72:73], v[68:69], v[68:69]
	v_mul_f32_e32 v127, 0xbfb8aa3b, v66
	v_exp_f32_e32 v127, v127
	v_mul_f32_e32 v136, 0xbfb8aa3b, v67
	v_exp_f32_e32 v137, v136
	v_pk_mul_f32 v[146:147], v[70:71], v[70:71]
	v_add_f32_e32 v127, 1.0, v127
	v_rcp_f32_e32 v136, v127
	v_add_f32_e32 v127, 1.0, v137
	v_rcp_f32_e32 v137, v127
	v_add_f32_e32 v72, v72, v73
	v_pk_mul_f32 v[64:65], v[74:75], v[64:65]
	v_add_f32_e32 v72, v146, v72
	v_pk_mul_f32 v[74:75], v[64:65], v[64:65]
	v_add_f32_e32 v72, v147, v72
	v_pk_mul_f32 v[66:67], v[66:67], v[136:137]
	v_add_f32_e32 v72, v74, v72
	v_pk_mul_f32 v[136:137], v[66:67], v[66:67]
	v_add_f32_e32 v72, v75, v72
	v_add_f32_e32 v72, v136, v72
	v_add_f32_e32 v72, v137, v72
	v_mov_b32_e32 v73, v36
	v_cmp_ne_u32_e64 s[6:7], 2, v130
	v_add_f32_dpp v72, v72, v72 quad_perm:[1,0,3,2] row_mask:0xf bank_mask:0xf bound_ctrl:1
	v_add_u32_e32 v132, s76, v37
	v_add_u32_e32 v130, 0, v129
	v_add_f32_dpp v72, v72, v72 quad_perm:[2,3,0,1] row_mask:0xf bank_mask:0xf bound_ctrl:1
	v_add_u32_e32 v128, s77, v37
	v_cndmask_b32_e64 v37, 1.0, v156, s[8:9]
	v_add_f32_dpp v72, v72, v72 row_half_mirror row_mask:0xf bank_mask:0xf bound_ctrl:1
	s_nop 1
	v_mov_b32_dpp v73, v72 row_mirror row_mask:0xf bank_mask:0xf
	s_and_saveexec_b64 s[8:9], s[6:7]
	s_xor_b64 s[64:65], exec, s[8:9]
	s_cbranch_execz .LBB0_248
	v_add_f32_e32 v72, v72, v73
	v_add_f32_e32 v72, 0x358637bd, v72
	v_mul_f32_e32 v73, 0x4b800000, v72
	v_cmp_gt_f32_e64 s[8:9], s79, v72
	s_nop 1
	v_cndmask_b32_e64 v72, v72, v73, s[8:9]
	v_rsq_f32_e32 v72, v72
	s_nop 0
	v_mul_f32_e32 v73, 0x45800000, v72
	v_cndmask_b32_e64 v72, v72, v73, s[8:9]
	v_mul_f32_e32 v72, v37, v72
	v_pk_mul_f32 v[68:69], v[68:69], v[72:73] op_sel_hi:[1,0]
	v_pk_mul_f32 v[70:71], v[70:71], v[72:73] op_sel_hi:[1,0]
	v_pk_mul_f32 v[64:65], v[64:65], v[72:73] op_sel_hi:[1,0]
	v_pk_mul_f32 v[66:67], v[66:67], v[72:73] op_sel_hi:[1,0]
	v_cvt_pk_bf16_f32 v72, v68, v69
	v_cvt_pk_bf16_f32 v73, v70, v71
	v_cvt_pk_bf16_f32 v74, v64, v65
	s_nop 0
	v_cvt_pk_bf16_f32 v75, v66, v67
	s_and_saveexec_b64 s[8:9], vcc
	s_xor_b64 s[8:9], exec, s[8:9]
	s_cbranch_execz .LBB0_245
	v_mad_u64_u32 v[136:137], s[66:67], v125, s80, v[132:133]
	ds_write_b128 v136, v[72:75]
	v_mad_u64_u32 v[72:73], s[66:67], v125, s81, v[130:131]
	ds_write_b128 v72, v[68:71] offset:33792
	ds_write_b128 v72, v[64:67] offset:33808

.LBB0_306:
	s_or_b64 exec, exec, s[6:7]
	s_waitcnt vmcnt(0)
	v_mov_b64_e32 v[32:33], v[120:121]
	v_mov_b64_e32 v[40:41], v[116:117]
	v_mov_b64_e32 v[44:45], v[112:113]
	v_mov_b64_e32 v[48:49], v[108:109]
	v_mov_b64_e32 v[52:53], v[104:105]
	v_mov_b64_e32 v[56:57], v[100:101]
	v_mov_b64_e32 v[60:61], v[96:97]
	v_mov_b64_e32 v[64:65], v[84:85]
	v_mov_b64_e32 v[68:69], v[80:81]
	v_mov_b64_e32 v[76:77], v[88:89]
	v_mov_b64_e32 v[72:73], v[92:93]
	v_mov_b64_e32 v[34:35], v[122:123]
	v_mov_b64_e32 v[42:43], v[118:119]
	v_mov_b64_e32 v[46:47], v[114:115]
	v_mov_b64_e32 v[50:51], v[110:111]
	v_mov_b64_e32 v[54:55], v[106:107]
	v_mov_b64_e32 v[58:59], v[102:103]
	v_mov_b64_e32 v[62:63], v[98:99]
	v_mov_b64_e32 v[66:67], v[86:87]
	v_mov_b64_e32 v[70:71], v[82:83]
	v_mov_b64_e32 v[78:79], v[90:91]
	v_mov_b64_e32 v[74:75], v[94:95]

.LBB0_582:
	s_mov_b32 s3, 0
	s_lshl_b64 s[54:55], s[2:3], 19
	s_add_u32 s7, s34, s54
	s_addc_u32 s16, s35, s55
	s_lshl_b32 s6, s2, 20
	s_mul_i32 s71, s2, 0x1c0000
	s_lshl_b32 s4, s2, 5
	s_and_b32 s0, s6, 0x1c00000
	s_mul_hi_u32 s70, s2, 0x1c0000
	s_mov_b32 s5, s3
	s_add_u32 s17, s30, s71
	s_addc_u32 s18, s31, s70
	s_lshl_b64 s[4:5], s[4:5], 2
	s_add_u32 s4, s48, s4
	s_addc_u32 s5, s49, s5
	s_lshl_b32 s6, s44, 10
	v_lshlrev_b32_e32 v48, 2, v56
	v_mov_b32_e32 v49, 0
	s_add_i32 s72, s6, 0xffff2000
	v_lshl_add_u64 v[0:1], s[4:5], 0, v[48:49]
	s_add_u32 s5, s7, s72
	s_addc_u32 s20, s16, 0
	s_ashr_i32 s65, s6, 31
	s_add_u32 s21, s17, s6
	s_addc_u32 s22, s18, s65
	s_add_i32 s56, s6, 0x2000
	s_add_i32 s23, s6, 0
	s_ashr_i32 s64, s56, 31
	s_add_u32 s26, s17, s56
	s_addc_u32 s27, s18, s64
	s_add_i32 s74, s6, 0xffff4000
	s_add_u32 s36, s7, s74
	s_addc_u32 s37, s16, 0
	s_add_i32 s66, s6, 0x4000
	s_add_i32 s38, s23, 0x2000
	s_ashr_i32 s67, s66, 31
	s_add_u32 s39, s17, s66
	s_addc_u32 s42, s18, s67
	s_add_i32 s78, s6, 0xffff6000
	s_add_u32 s43, s7, s78
	s_addc_u32 s50, s16, 0
	s_add_i32 s68, s6, 0x6000
	s_add_i32 s51, s23, 0x4000
	s_ashr_i32 s69, s68, 31
	s_add_u32 s57, s17, s68
	s_addc_u32 s89, s18, s69
	s_add_i32 s80, s6, 0xffff8000
	s_mov_b32 s4, 0x1d0000
	s_add_u32 s91, s7, s80
	v_add_co_u32_e32 v0, vcc, s4, v0
	s_addc_u32 s96, s16, 0
	s_add_i32 s73, s6, 0x8000
	v_addc_co_u32_e32 v1, vcc, 0, v1, vcc
	s_add_i32 s97, s23, 0x6000
	s_ashr_i32 s75, s73, 31
	s_add_u32 vcc_lo, s17, s73
	s_addc_u32 vcc_hi, s18, s75
	s_add_i32 s82, s6, 0xffffa000
	s_add_u32 s76, s7, s82
	s_mov_b32 s90, s44
	s_addc_u32 s44, s16, 0
	s_add_i32 s79, s6, 0xa000
	s_add_i32 s45, s23, 0x8000
	s_ashr_i32 s81, s79, 31
	s_add_u32 s87, s17, s79
	s_addc_u32 s46, s18, s81
	s_add_i32 s84, s6, 0xffffc000
	s_add_u32 s47, s7, s84
	s_addc_u32 s86, s16, 0
	s_add_i32 s83, s6, 0xc000
	v_writelane_b32 v233, s52, 36
	s_add_i32 s8, s23, 0xa000
	s_ashr_i32 s85, s83, 31
	v_writelane_b32 v233, s53, 37
	s_add_u32 s9, s17, s83
	v_writelane_b32 v233, s0, 38
	s_addc_u32 s0, s18, s85
	s_add_i32 s88, s6, 0xffffe000
	s_add_u32 s1, s7, s88
	s_addc_u32 s52, s16, 0
	s_add_i32 s53, s23, 0xc000
	s_add_u32 s58, s7, s6
	s_addc_u32 s59, s16, 0
	s_add_i32 s14, s23, 0xe000
	s_add_i32 s4, s6, 0x10000
	s_add_u32 s60, s7, s56
	s_addc_u32 s61, s16, 0
	s_add_i32 s15, s23, 0x10000
	s_add_u32 s12, s7, 0x4000
	s_addc_u32 s13, s16, 0
	s_add_u32 s7, s17, 0xe000
	s_addc_u32 s24, s18, 0
	s_add_u32 s25, s7, s6
	s_addc_u32 s62, s24, s65
	s_add_u32 s92, s12, s72
	s_addc_u32 s63, s13, 0
	s_cmpk_lt_u32 s33, 0xe00
	s_cselect_b64 s[16:17], -1, 0
	s_and_b64 s[18:19], s[16:17], exec
	s_cselect_b32 s19, s22, s20
	s_cselect_b32 s18, s21, s5
	s_cselect_b32 s63, s62, s63
	s_cselect_b32 s62, s25, s92
	s_add_i32 s5, 0, 0x12000
	s_add_i32 s25, s5, s6
	s_add_u32 s22, s7, s56
	s_mov_b32 m0, s23
	s_addc_u32 s23, s24, s64
	s_add_u32 s92, s12, s74
	s_addc_u32 s93, s13, 0
	v_lshlrev_b32_e32 v48, 4, v218
	s_cmpk_lt_u32 s33, 0xc00
	global_load_lds_dwordx4 v48, s[18:19]
	s_cselect_b64 s[18:19], -1, 0
	s_and_b64 s[20:21], s[18:19], exec
	s_cselect_b32 s21, s27, s37
	s_cselect_b32 s20, s26, s36
	s_cselect_b32 s92, s22, s92
	s_cselect_b32 s93, s23, s93
	s_add_i32 s10, s5, s56
	s_add_u32 s11, s7, s66
	s_addc_u32 s26, s24, s67
	s_add_u32 s27, s12, s78
	s_addc_u32 s36, s13, 0
	s_mov_b32 m0, s38
	s_cmpk_lt_u32 s33, 0xa00
	global_load_lds_dwordx4 v48, s[20:21]
	s_cselect_b64 s[20:21], -1, 0
	s_and_b64 s[22:23], s[20:21], exec
	s_cselect_b32 s23, s42, s50
	s_cselect_b32 s22, s39, s43
	s_cselect_b32 s95, s26, s36
	s_cselect_b32 s94, s11, s27
	s_add_i32 s11, s5, s66
	s_add_u32 s36, s7, s68
	s_addc_u32 s37, s24, s69
	s_add_u32 s38, s12, s80
	s_addc_u32 s39, s13, 0
	s_mov_b32 m0, s51
	s_cmpk_lt_u32 s33, 0x800
	global_load_lds_dwordx4 v48, s[22:23]
	s_cselect_b64 s[22:23], -1, 0
	s_and_b64 s[26:27], s[22:23], exec
	s_cselect_b32 s27, s89, s96
	s_cselect_b32 s26, s57, s91
	s_mov_b32 m0, s97
	s_cselect_b32 s96, s36, s38
	s_cselect_b32 s97, s37, s39
	s_add_i32 s89, s5, s68
	s_add_u32 s38, s7, s73
	s_addc_u32 s39, s24, s75
	s_add_u32 s42, s12, s82
	s_addc_u32 s43, s13, 0
	s_cmpk_lt_u32 s33, 0x600
	global_load_lds_dwordx4 v48, s[26:27]
	s_cselect_b64 s[26:27], -1, 0
	s_and_b64 s[36:37], s[26:27], exec
	s_cselect_b32 s37, vcc_hi, s44
	s_cselect_b32 s36, vcc_lo, s76
	s_cselect_b32 vcc_hi, s39, s43
	s_cselect_b32 vcc_lo, s38, s42
	s_add_i32 s91, s5, s73
	s_add_u32 s42, s7, s79
	s_addc_u32 s43, s24, s81
	s_add_u32 s44, s12, s84
	s_mov_b32 m0, s45
	s_addc_u32 s45, s13, 0
	s_cmpk_lt_u32 s33, 0x400
	global_load_lds_dwordx4 v48, s[36:37]
	s_cselect_b64 s[36:37], -1, 0
	s_and_b64 s[38:39], s[36:37], exec
	s_cselect_b32 s39, s46, s86
	s_cselect_b32 s38, s87, s47
	s_mov_b32 m0, s8
	s_cselect_b32 s50, s42, s44
	s_cselect_b32 s51, s43, s45
	s_add_i32 s8, s5, s79
	s_add_u32 s44, s7, s83
	s_addc_u32 s24, s24, s85
	s_add_u32 s45, s12, s88
	s_addc_u32 s46, s13, 0
	s_cmpk_lt_u32 s33, 0x200
	global_load_lds_dwordx4 v48, s[38:39]
	s_cselect_b64 s[38:39], -1, 0
	s_and_b64 s[42:43], s[38:39], exec
	s_cselect_b32 s43, s0, s52
	s_cselect_b32 s42, s9, s1
	s_mov_b32 m0, s53
	global_load_dword v57, v[0:1], off
	s_mov_b32 s7, s3
	global_load_lds_dwordx4 v48, s[42:43]
	s_mov_b32 m0, s14
	s_mov_b32 s57, s3
	global_load_lds_dwordx4 v48, s[58:59]
	s_mov_b32 m0, s15
	v_or_b32_e32 v0, s54, v48
	global_load_lds_dwordx4 v48, s[60:61]
	s_mov_b32 m0, s25
	v_mov_b32_e32 v1, s55
	global_load_lds_dwordx4 v48, s[62:63]
	s_mov_b32 m0, s10
	v_lshl_add_u64 v[2:3], v[0:1], 0, s[6:7]
	global_load_lds_dwordx4 v48, s[92:93]
	s_mov_b32 m0, s11
	v_lshl_add_u64 v[0:1], v[0:1], 0, s[56:57]
	global_load_lds_dwordx4 v48, s[94:95]
	s_mov_b32 m0, s89
	v_readlane_b32 s7, v233, 38
	global_load_lds_dwordx4 v48, s[96:97]
	s_mov_b32 m0, s91
	s_mov_b64 s[42:43], 0x4000
	global_load_lds_dwordx4 v48, vcc
	s_mov_b32 m0, s8
	v_mov_b32_e32 v4, v49
	global_load_lds_dwordx4 v48, s[50:51]
	s_cselect_b32 s51, s24, s46
	s_cselect_b32 s50, s44, s45
	s_add_i32 m0, s5, s83
	s_mov_b32 s44, s90
	global_load_lds_dwordx4 v48, s[50:51]
	s_add_u32 s50, s12, s6
	s_addc_u32 s51, s13, 0
	s_add_i32 m0, s25, 0xe000
	v_mov_b32_e32 v5, v49
	global_load_lds_dwordx4 v48, s[50:51]
	s_add_u32 s50, s12, s56
	s_addc_u32 s51, s13, 0
	s_add_i32 m0, s5, s4
	s_lshl_b32 s5, s90, 11
	global_load_lds_dwordx4 v48, s[50:51]
	s_add_u32 s0, s71, s6
	s_addc_u32 s1, s70, s65
	s_add_u32 s0, s30, s0
	s_addc_u32 s1, s31, s1
	s_add_u32 s58, s0, 0x1c000
	s_addc_u32 s59, s1, 0
	s_add_u32 s0, s71, s56
	s_addc_u32 s1, s70, s64
	s_add_u32 s0, s30, s0
	s_addc_u32 s1, s31, s1
	s_add_u32 s60, s0, 0x1c000
	s_addc_u32 s61, s1, 0
	s_add_u32 s0, s71, s66
	s_addc_u32 s1, s70, s67
	s_add_u32 s0, s30, s0
	s_addc_u32 s1, s31, s1
	s_add_u32 s62, s0, 0x1c000
	s_addc_u32 s63, s1, 0
	s_add_u32 s0, s71, s68
	s_addc_u32 s1, s70, s69
	s_add_u32 s0, s30, s0
	s_addc_u32 s1, s31, s1
	s_add_u32 s64, s0, 0x1c000
	s_addc_u32 s65, s1, 0
	s_add_u32 s0, s71, s73
	s_addc_u32 s1, s70, s75
	s_add_u32 s0, s30, s0
	s_addc_u32 s1, s31, s1
	s_add_u32 s66, s0, 0x1c000
	s_addc_u32 s67, s1, 0
	s_add_u32 s0, s71, s79
	s_addc_u32 s1, s70, s81
	s_add_u32 s0, s30, s0
	s_addc_u32 s1, s31, s1
	s_add_u32 s68, s0, 0x1c000
	s_addc_u32 s69, s1, 0
	s_add_u32 s0, s71, s83
	s_addc_u32 s1, s70, s85
	s_add_u32 s0, s30, s0
	s_addc_u32 s1, s31, s1
	s_add_u32 s70, s0, 0x1c000
	s_addc_u32 s71, s1, 0
	s_add_u32 s0, s54, s72
	s_addc_u32 s1, s55, 0
	s_add_u32 s72, s0, 0x1c08000
	s_addc_u32 s73, s1, 0
	s_add_u32 s0, s54, s74
	s_addc_u32 s1, s55, 0
	s_add_u32 s74, s0, 0x1c08000
	s_addc_u32 s75, s1, 0
	s_add_u32 s0, s54, s78
	s_addc_u32 s1, s55, 0
	s_add_u32 s78, s0, 0x1c08000
	s_addc_u32 s79, s1, 0
	s_add_u32 s0, s54, s80
	s_addc_u32 s1, s55, 0
	s_add_u32 s80, s0, 0x1c08000
	s_addc_u32 s81, s1, 0
	s_add_u32 s0, s54, s82
	s_addc_u32 s1, s55, 0
	s_add_u32 s82, s0, 0x1c08000
	s_addc_u32 s83, s1, 0
	s_add_u32 s0, s54, s84
	s_addc_u32 s1, s55, 0
	s_add_u32 s84, s0, 0x1c08000
	s_addc_u32 s85, s1, 0
	s_add_u32 s0, s54, s88
	s_addc_u32 s1, s55, 0
	s_add_u32 s88, s0, 0x1c08000
	s_addc_u32 s89, s1, 0
	s_and_b32 s0, s2, 3
	s_lshl_b32 s0, s0, 9
	s_and_b32 s1, s33, 0xffffffc0
	s_add_u32 s0, s1, s0
	s_mov_b64 s[50:51], 0x1c08000
	s_addc_u32 s1, 0, 0
	v_lshl_add_u64 v[50:51], v[2:3], 0, s[50:51]
	v_lshl_add_u64 v[52:53], v[0:1], 0, s[50:51]
	v_lshlrev_b32_e32 v0, 9, v188
	s_add_u32 s50, s0, s7
	s_waitcnt vmcnt(0)
	v_and_b32_e32 v0, 0x6000, v0
	v_mov_b32_e32 v1, v49
	s_addc_u32 s51, s1, 0
	v_lshl_add_u64 v[54:55], s[50:51], 0, v[0:1]
	v_lshl_or_b32 v54, v165, 2, v54
	s_mov_b64 s[54:55], 0
	v_mov_b32_e32 v0, v49
	v_mov_b32_e32 v2, v49
	v_mov_b32_e32 v3, v49
	v_mov_b32_e32 v6, v49
	v_mov_b32_e32 v7, v49
	v_mov_b32_e32 v8, v49
	v_mov_b32_e32 v9, v49
	v_mov_b32_e32 v10, v49
	v_mov_b32_e32 v11, v49
	v_mov_b32_e32 v12, v49
	v_mov_b32_e32 v13, v49
	v_mov_b32_e32 v14, v49
	v_mov_b32_e32 v15, v49
	v_mov_b32_e32 v16, v49
	v_mov_b32_e32 v17, v49
	v_mov_b32_e32 v18, v49
	v_mov_b32_e32 v19, v49
	v_mov_b32_e32 v20, v49
	v_mov_b32_e32 v21, v49
	v_mov_b32_e32 v22, v49
	v_mov_b32_e32 v23, v49
	v_mov_b32_e32 v28, v49
	v_mov_b32_e32 v29, v49
	v_mov_b32_e32 v30, v49
	v_mov_b32_e32 v31, v49
	v_mov_b32_e32 v24, v49
	v_mov_b32_e32 v25, v49
	v_mov_b32_e32 v26, v49
	v_mov_b32_e32 v27, v49
	s_waitcnt vmcnt(0) lgkmcnt(0)
	s_barrier
	s_lshl_b32 s6, s44, 10
	s_mul_i32 s1, s2, 0x1c0000
	s_add_u32 s1, s1, s6
	s_add_u32 s1, s1, 0x1c000
	s_add_u32 s10, s30, s1
	s_addc_u32 s11, s31, 0
	s_lshl_b32 s1, s2, 19
	s_add_u32 s1, s1, s6
	s_add_u32 s1, s1, 0x8000
	s_add_u32 s12, s34, s1
	s_addc_u32 s13, s35, 0
	s_lshr_b32 s1, s2, 2
	s_lshl_b32 s1, s1, 22
	s_add_u32 s1, s1, 0xcc00000
	s_add_u32 s14, s48, s1
	s_addc_u32 s15, s49, 0
	s_and_b32 s0, s2, 3
	s_lshl_b32 s0, s0, 9
	s_lshl_b32 s1, s44, 6
	s_add_i32 s0, s0, s1
	v_lshlrev_b32_e32 v190, 9, v188
	v_and_b32_e32 v190, 0x6000, v190
	v_and_b32_e32 v191, 3, v188
	v_lshl_or_b32 v190, v191, 11, v190
	v_and_b32_e32 v191, 12, v188
	v_lshl_or_b32 v190, v191, 2, v190
	v_add_u32_e32 v190, s0, v190
	v_add_u32_e32 v191, 0x8000, v190
	v_add_u32_e32 v192, 0x10000, v190
	v_add_u32_e32 v193, 0x18000, v190
	s_mov_b32 s16, 0x55555555
	s_mov_b32 s17, 0x55555555
	s_mov_b32 s18, 0xaaaaaaaa
	s_mov_b32 s19, 0xaaaaaaaa
	s_mov_b32 s20, 0x33333333
	s_mov_b32 s21, 0x33333333
	s_mov_b32 s22, 0xcccccccc
	s_mov_b32 s23, 0xcccccccc
	v_add_u32_e32 v181, 0x2000, v48
	v_add_u32_e32 v182, 0x4000, v48
	v_add_u32_e32 v183, 0x6000, v48
	v_add_u32_e32 v184, 0x8000, v48
	v_add_u32_e32 v185, 0xa000, v48
	v_add_u32_e32 v186, 0xc000, v48
	v_mov_b32_e32 v93, v48
	v_add_u32_e32 v94, s5, v161
	s_mov_b32 s3, 0
	s_mov_b32 s8, 0x12000
	s_mov_b32 s9, 0
	ds_read_b128 v[120:123], v93 offset:6144
	ds_read_b128 v[124:127], v93 offset:7168
	ds_read_b128 v[128:131], v93 offset:8192
	ds_read_b128 v[132:135], v93 offset:9216
	ds_read_b128 v[136:139], v93 offset:10240
	ds_read_b128 v[140:143], v93 offset:11264
	ds_read_b128 v[96:99], v93
	ds_read_b128 v[100:103], v93 offset:1024
	ds_read_b128 v[104:107], v93 offset:2048
	ds_read_b128 v[108:111], v93 offset:3072
	ds_read_b128 v[112:115], v93 offset:4096
	ds_read_b128 v[116:119], v93 offset:5120
	ds_read2st64_b64 v[172:175], v94 offset0:112 offset1:113
	ds_read2st64_b64 v[176:179], v94 offset0:114 offset1:115
.Lscan_loop:
	v_readlane_b32 s56, v57, s3
	v_cvt_pk_bf16_f32 v144, v0, v1
	v_cvt_pk_bf16_f32 v145, v2, v3
	v_cvt_pk_bf16_f32 v146, v4, v5
	v_cvt_pk_bf16_f32 v147, v6, v7
	v_cvt_pk_bf16_f32 v148, v8, v9
	v_cvt_pk_bf16_f32 v149, v10, v11
	v_cvt_pk_bf16_f32 v150, v12, v13
	v_cvt_pk_bf16_f32 v151, v14, v15
	s_waitcnt lgkmcnt(7)
	v_mfma_f32_16x16x32_bf16 v[64:67], v[96:99], v[144:147], 0
	ds_read_b128 v[96:99], v93 offset:12288
	v_cvt_pk_bf16_f32 v152, v16, v17
	v_cvt_pk_bf16_f32 v153, v18, v19
	v_cvt_pk_bf16_f32 v154, v20, v21
	v_cvt_pk_bf16_f32 v155, v22, v23
	s_waitcnt lgkmcnt(7)
	v_mfma_f32_16x16x32_bf16 v[64:67], v[100:103], v[148:151], v[64:67]
	ds_read_b128 v[100:103], v93 offset:13312
	v_cvt_pk_bf16_f32 v156, v28, v29
	v_cvt_pk_bf16_f32 v157, v30, v31
	v_cvt_pk_bf16_f32 v158, v24, v25
	v_cvt_pk_bf16_f32 v159, v26, v27
	s_waitcnt lgkmcnt(7)
	v_mfma_f32_16x16x32_bf16 v[64:67], v[104:107], v[152:155], v[64:67]
	ds_read_b128 v[104:107], v93 offset:14336
	v_mul_f32_e32 v0, s56, v0
	v_mul_f32_e32 v1, s56, v1
	s_waitcnt lgkmcnt(7)
	v_mfma_f32_16x16x32_bf16 v[64:67], v[108:111], v[156:159], v[64:67]
	ds_read_b128 v[108:111], v93 offset:15360
	v_mul_f32_e32 v2, s56, v2
	v_mul_f32_e32 v3, s56, v3
	s_waitcnt lgkmcnt(7)
	v_mfma_f32_16x16x32_bf16 v[68:71], v[112:115], v[144:147], 0
	ds_read_b128 v[112:115], v93 offset:16384
	v_mul_f32_e32 v4, s56, v4
	v_mul_f32_e32 v5, s56, v5
	s_waitcnt lgkmcnt(7)
	v_mfma_f32_16x16x32_bf16 v[68:71], v[116:119], v[148:151], v[68:71]
	ds_read_b128 v[116:119], v93 offset:17408
	v_mul_f32_e32 v6, s56, v6
	v_mul_f32_e32 v7, s56, v7
	v_mfma_f32_16x16x32_bf16 v[68:71], v[120:123], v[152:155], v[68:71]
	ds_read_b128 v[120:123], v93 offset:18432
	v_mul_f32_e32 v8, s56, v8
	v_mul_f32_e32 v9, s56, v9
	v_mfma_f32_16x16x32_bf16 v[68:71], v[124:127], v[156:159], v[68:71]
	ds_read_b128 v[124:127], v93 offset:19456
	v_mul_f32_e32 v10, s56, v10
	v_mul_f32_e32 v11, s56, v11
	v_mfma_f32_16x16x32_bf16 v[72:75], v[128:131], v[144:147], 0
	ds_read_b128 v[128:131], v93 offset:20480
	v_mul_f32_e32 v12, s56, v12
	v_mul_f32_e32 v13, s56, v13
	v_mfma_f32_16x16x32_bf16 v[72:75], v[132:135], v[148:151], v[72:75]
	ds_read_b128 v[132:135], v93 offset:21504
	v_mul_f32_e32 v14, s56, v14
	v_mul_f32_e32 v15, s56, v15
	v_mfma_f32_16x16x32_bf16 v[72:75], v[136:139], v[152:155], v[72:75]
	ds_read_b128 v[136:139], v93 offset:22528
	v_mul_f32_e32 v16, s56, v16
	v_mul_f32_e32 v17, s56, v17
	v_mfma_f32_16x16x32_bf16 v[72:75], v[140:143], v[156:159], v[72:75]
	ds_read_b128 v[140:143], v93 offset:23552
	v_mul_f32_e32 v18, s56, v18
	v_mul_f32_e32 v19, s56, v19
	s_waitcnt lgkmcnt(11)
	v_mfma_f32_16x16x32_bf16 v[76:79], v[96:99], v[144:147], 0
	ds_read_b128 v[96:99], v93 offset:24576
	v_lshlrev_b32_e32 v88, 16, v172
	v_and_b32_e32 v89, 0xffff0000, v172
	v_sub_f32_e32 v64, v88, v64
	v_sub_f32_e32 v65, v89, v65
	s_waitcnt lgkmcnt(11)
	v_mfma_f32_16x16x32_bf16 v[76:79], v[100:103], v[148:151], v[76:79]
	ds_read_b128 v[100:103], v93 offset:25600
	v_lshlrev_b32_e32 v88, 16, v173
	v_and_b32_e32 v89, 0xffff0000, v173
	v_sub_f32_e32 v66, v88, v66
	v_sub_f32_e32 v67, v89, v67
	s_waitcnt lgkmcnt(11)
	v_mfma_f32_16x16x32_bf16 v[76:79], v[104:107], v[152:155], v[76:79]
	ds_read_b128 v[104:107], v93 offset:26624
	v_lshlrev_b32_e32 v88, 16, v174
	v_and_b32_e32 v89, 0xffff0000, v174
	v_sub_f32_e32 v68, v88, v68
	v_sub_f32_e32 v69, v89, v69
	s_waitcnt lgkmcnt(11)
	v_mfma_f32_16x16x32_bf16 v[76:79], v[108:111], v[156:159], v[76:79]
	ds_read_b128 v[108:111], v93 offset:27648
	v_lshlrev_b32_e32 v88, 16, v175
	v_and_b32_e32 v89, 0xffff0000, v175
	v_sub_f32_e32 v70, v88, v70
	v_sub_f32_e32 v71, v89, v71
	s_waitcnt lgkmcnt(11)
	v_mfma_f32_16x16x32_bf16 v[32:35], v[112:115], v[144:147], 0
	ds_read_b128 v[112:115], v93 offset:28672
	v_cvt_pk_bf16_f32 v80, v64, v65
	v_cvt_pk_bf16_f32 v81, v66, v67
	v_cvt_pk_bf16_f32 v82, v68, v69
	v_cvt_pk_bf16_f32 v83, v70, v71
	s_waitcnt lgkmcnt(11)
	v_mfma_f32_16x16x32_bf16 v[32:35], v[116:119], v[148:151], v[32:35]
	ds_read_b128 v[116:119], v93 offset:29696
	v_lshlrev_b32_e32 v88, 16, v176
	v_and_b32_e32 v89, 0xffff0000, v176
	v_sub_f32_e32 v72, v88, v72
	v_sub_f32_e32 v73, v89, v73
	s_waitcnt lgkmcnt(11)
	v_mfma_f32_16x16x32_bf16 v[32:35], v[120:123], v[152:155], v[32:35]
	ds_read_b128 v[120:123], v93 offset:30720
	v_lshlrev_b32_e32 v88, 16, v177
	v_and_b32_e32 v89, 0xffff0000, v177
	v_sub_f32_e32 v74, v88, v74
	v_sub_f32_e32 v75, v89, v75
	s_waitcnt lgkmcnt(11)
	v_mfma_f32_16x16x32_bf16 v[32:35], v[124:127], v[156:159], v[32:35]
	ds_read_b128 v[124:127], v93 offset:31744
	v_lshlrev_b32_e32 v88, 16, v178
	v_and_b32_e32 v89, 0xffff0000, v178
	v_sub_f32_e32 v76, v88, v76
	v_sub_f32_e32 v77, v89, v77
	s_waitcnt lgkmcnt(11)
	v_mfma_f32_16x16x32_bf16 v[36:39], v[128:131], v[144:147], 0
	ds_read_b128 v[128:131], v93 offset:32768
	v_lshlrev_b32_e32 v88, 16, v179
	v_and_b32_e32 v89, 0xffff0000, v179
	v_sub_f32_e32 v78, v88, v78
	v_sub_f32_e32 v79, v89, v79
	s_waitcnt lgkmcnt(11)
	v_mfma_f32_16x16x32_bf16 v[36:39], v[132:135], v[148:151], v[36:39]
	ds_read_b128 v[132:135], v93 offset:34816
	v_cvt_pk_bf16_f32 v84, v72, v73
	v_cvt_pk_bf16_f32 v85, v74, v75
	v_cvt_pk_bf16_f32 v86, v76, v77
	v_cvt_pk_bf16_f32 v87, v78, v79
	s_waitcnt lgkmcnt(11)
	v_mfma_f32_16x16x32_bf16 v[36:39], v[136:139], v[152:155], v[36:39]
	ds_read_b128 v[136:139], v93 offset:36864
	v_mul_f32_e32 v20, s56, v20
	s_waitcnt lgkmcnt(11)
	v_mfma_f32_16x16x32_bf16 v[36:39], v[140:143], v[156:159], v[36:39]
	ds_read_b128 v[140:143], v93 offset:37888
	v_mul_f32_e32 v21, s56, v21
	s_waitcnt lgkmcnt(11)
	v_mfma_f32_16x16x32_bf16 v[40:43], v[96:99], v[144:147], 0
	ds_read_b128 v[96:99], v93 offset:38912
	v_mul_f32_e32 v22, s56, v22
	s_waitcnt lgkmcnt(11)
	v_mfma_f32_16x16x32_bf16 v[40:43], v[100:103], v[148:151], v[40:43]
	ds_read_b128 v[100:103], v93 offset:39936
	v_mul_f32_e32 v23, s56, v23
	s_waitcnt lgkmcnt(11)
	v_mfma_f32_16x16x32_bf16 v[40:43], v[104:107], v[152:155], v[40:43]
	ds_read_b128 v[104:107], v93 offset:40960
	v_mul_f32_e32 v24, s56, v24
	s_waitcnt lgkmcnt(11)
	v_mfma_f32_16x16x32_bf16 v[40:43], v[108:111], v[156:159], v[40:43]
	ds_read_b128 v[108:111], v93 offset:41984
	v_mul_f32_e32 v25, s56, v25
	s_waitcnt lgkmcnt(11)
	v_mfma_f32_16x16x32_bf16 v[44:47], v[112:115], v[144:147], 0
	ds_read_b128 v[112:115], v93 offset:43008
	v_mul_f32_e32 v26, s56, v26
	s_waitcnt lgkmcnt(11)
	v_mfma_f32_16x16x32_bf16 v[44:47], v[116:119], v[148:151], v[44:47]
	ds_read_b128 v[116:119], v93 offset:44032
	v_mul_f32_e32 v27, s56, v27
	s_waitcnt lgkmcnt(11)
	v_mfma_f32_16x16x32_bf16 v[44:47], v[120:123], v[152:155], v[44:47]
	ds_read_b128 v[120:123], v93 offset:45056
	v_mul_f32_e32 v28, s56, v28
	s_waitcnt lgkmcnt(11)
	v_mfma_f32_16x16x32_bf16 v[44:47], v[124:127], v[156:159], v[44:47]
	ds_read_b128 v[124:127], v93 offset:46080
	v_mul_f32_e32 v29, s56, v29
	s_waitcnt lgkmcnt(11)
	v_mfma_f32_16x16x32_bf16 v[32:35], v[128:131], v[80:83], v[32:35]
	ds_read_b128 v[128:131], v93 offset:47104
	v_mul_f32_e32 v30, s56, v30
	s_waitcnt lgkmcnt(11)
	v_mfma_f32_16x16x32_bf16 v[36:39], v[132:135], v[80:83], v[36:39]
	ds_read_b128 v[132:135], v93 offset:48128
	v_mul_f32_e32 v31, s56, v31
	s_waitcnt lgkmcnt(11)
	v_mfma_f32_16x16x32_bf16 v[40:43], v[136:139], v[80:83], v[40:43]
	ds_read_b128 v[136:139], v93 offset:49152
	s_waitcnt lgkmcnt(11)
	v_mfma_f32_16x16x32_bf16 v[40:43], v[140:143], v[84:87], v[40:43]
	ds_read_b128 v[140:143], v93 offset:50176
	s_waitcnt lgkmcnt(11)
	v_mfma_f32_16x16x32_bf16 v[44:47], v[96:99], v[80:83], v[44:47]
	ds_read_b128 v[96:99], v93 offset:51200
	s_waitcnt lgkmcnt(11)
	v_mfma_f32_16x16x32_bf16 v[44:47], v[100:103], v[84:87], v[44:47]
	ds_read_b128 v[100:103], v93 offset:52224
	s_waitcnt lgkmcnt(11)
	v_mfma_f32_16x16x32_bf16 v[0:3], v[104:107], v[80:83], v[0:3]
	ds_read_b128 v[104:107], v93 offset:53248
	s_waitcnt lgkmcnt(11)
	v_mfma_f32_16x16x32_bf16 v[0:3], v[108:111], v[84:87], v[0:3]
	ds_read_b128 v[108:111], v93 offset:54272
	s_waitcnt lgkmcnt(11)
	v_mfma_f32_16x16x32_bf16 v[4:7], v[112:115], v[80:83], v[4:7]
	ds_read_b128 v[112:115], v93 offset:55296
	s_mov_b64 vcc, s[16:17]
	v_cndmask_b32_dpp v200, v33, v32, vcc quad_perm:[1,0,3,2] row_mask:0xf bank_mask:0xf
	v_cndmask_b32_dpp v202, v35, v34, vcc quad_perm:[1,0,3,2] row_mask:0xf bank_mask:0xf
	v_cndmask_b32_dpp v204, v37, v36, vcc quad_perm:[1,0,3,2] row_mask:0xf bank_mask:0xf
	v_cndmask_b32_dpp v206, v39, v38, vcc quad_perm:[1,0,3,2] row_mask:0xf bank_mask:0xf
	s_waitcnt lgkmcnt(11)
	v_mfma_f32_16x16x32_bf16 v[4:7], v[116:119], v[84:87], v[4:7]
	ds_read_b128 v[116:119], v93 offset:56320
	s_mov_b64 vcc, s[18:19]
	v_cndmask_b32_dpp v201, v32, v33, vcc quad_perm:[1,0,3,2] row_mask:0xf bank_mask:0xf
	v_cndmask_b32_dpp v203, v34, v35, vcc quad_perm:[1,0,3,2] row_mask:0xf bank_mask:0xf
	v_cndmask_b32_dpp v205, v36, v37, vcc quad_perm:[1,0,3,2] row_mask:0xf bank_mask:0xf
	v_cndmask_b32_dpp v207, v38, v39, vcc quad_perm:[1,0,3,2] row_mask:0xf bank_mask:0xf
	s_waitcnt lgkmcnt(11)
	v_mfma_f32_16x16x32_bf16 v[8:11], v[120:123], v[80:83], v[8:11]
	s_mov_b64 vcc, s[20:21]
	v_cndmask_b32_dpp v52, v202, v200, vcc quad_perm:[2,3,0,1] row_mask:0xf bank_mask:0xf
	v_cndmask_b32_dpp v53, v203, v201, vcc quad_perm:[2,3,0,1] row_mask:0xf bank_mask:0xf
	v_cndmask_b32_dpp v58, v206, v204, vcc quad_perm:[2,3,0,1] row_mask:0xf bank_mask:0xf
	v_cndmask_b32_dpp v59, v207, v205, vcc quad_perm:[2,3,0,1] row_mask:0xf bank_mask:0xf
	v_add_u32_e32 v93, s8, v93
	v_add_u32_e32 v94, s8, v94
	s_sub_i32 s8, 0, s8
	s_waitcnt lgkmcnt(10)
	v_mfma_f32_16x16x32_bf16 v[8:11], v[124:127], v[84:87], v[8:11]
	s_mov_b64 vcc, s[22:23]
	v_cndmask_b32_dpp v54, v200, v202, vcc quad_perm:[2,3,0,1] row_mask:0xf bank_mask:0xf
	v_cndmask_b32_dpp v55, v201, v203, vcc quad_perm:[2,3,0,1] row_mask:0xf bank_mask:0xf
	v_cndmask_b32_dpp v60, v204, v206, vcc quad_perm:[2,3,0,1] row_mask:0xf bank_mask:0xf
	v_cndmask_b32_dpp v61, v205, v207, vcc quad_perm:[2,3,0,1] row_mask:0xf bank_mask:0xf
	s_waitcnt lgkmcnt(9)
	v_mfma_f32_16x16x32_bf16 v[12:15], v[128:131], v[80:83], v[12:15]
	global_store_dwordx4 v190, v[52:55], s[14:15]
	global_store_dwordx4 v191, v[58:61], s[14:15]
	s_mov_b64 vcc, s[16:17]
	v_cndmask_b32_dpp v208, v41, v40, vcc quad_perm:[1,0,3,2] row_mask:0xf bank_mask:0xf
	v_cndmask_b32_dpp v210, v43, v42, vcc quad_perm:[1,0,3,2] row_mask:0xf bank_mask:0xf
	v_cndmask_b32_dpp v212, v45, v44, vcc quad_perm:[1,0,3,2] row_mask:0xf bank_mask:0xf
	v_cndmask_b32_dpp v214, v47, v46, vcc quad_perm:[1,0,3,2] row_mask:0xf bank_mask:0xf
	s_waitcnt lgkmcnt(8)
	v_mfma_f32_16x16x32_bf16 v[12:15], v[132:135], v[84:87], v[12:15]
	s_mov_b64 vcc, s[18:19]
	v_cndmask_b32_dpp v209, v40, v41, vcc quad_perm:[1,0,3,2] row_mask:0xf bank_mask:0xf
	v_cndmask_b32_dpp v211, v42, v43, vcc quad_perm:[1,0,3,2] row_mask:0xf bank_mask:0xf
	v_cndmask_b32_dpp v213, v44, v45, vcc quad_perm:[1,0,3,2] row_mask:0xf bank_mask:0xf
	v_cndmask_b32_dpp v215, v46, v47, vcc quad_perm:[1,0,3,2] row_mask:0xf bank_mask:0xf
	s_waitcnt lgkmcnt(7)
	v_mfma_f32_16x16x32_bf16 v[16:19], v[136:139], v[80:83], v[16:19]
	s_mov_b64 vcc, s[20:21]
	v_cndmask_b32_dpp v220, v210, v208, vcc quad_perm:[2,3,0,1] row_mask:0xf bank_mask:0xf
	v_cndmask_b32_dpp v221, v211, v209, vcc quad_perm:[2,3,0,1] row_mask:0xf bank_mask:0xf
	v_cndmask_b32_dpp v224, v214, v212, vcc quad_perm:[2,3,0,1] row_mask:0xf bank_mask:0xf
	v_cndmask_b32_dpp v225, v215, v213, vcc quad_perm:[2,3,0,1] row_mask:0xf bank_mask:0xf
	s_waitcnt lgkmcnt(6)
	v_mfma_f32_16x16x32_bf16 v[16:19], v[140:143], v[84:87], v[16:19]
	s_mov_b64 vcc, s[22:23]
	v_cndmask_b32_dpp v222, v208, v210, vcc quad_perm:[2,3,0,1] row_mask:0xf bank_mask:0xf
	v_cndmask_b32_dpp v223, v209, v211, vcc quad_perm:[2,3,0,1] row_mask:0xf bank_mask:0xf
	v_cndmask_b32_dpp v226, v212, v214, vcc quad_perm:[2,3,0,1] row_mask:0xf bank_mask:0xf
	v_cndmask_b32_dpp v227, v213, v215, vcc quad_perm:[2,3,0,1] row_mask:0xf bank_mask:0xf
	s_nop 0
	global_store_dwordx4 v192, v[220:223], s[14:15]
	global_store_dwordx4 v193, v[224:227], s[14:15]
	s_waitcnt lgkmcnt(0)
	s_waitcnt vmcnt(4)
	s_barrier
	ds_read_b128 v[120:123], v93 offset:6144
	ds_read_b128 v[124:127], v93 offset:7168
	ds_read_b128 v[128:131], v93 offset:8192
	ds_read_b128 v[132:135], v93 offset:9216
	ds_read_b128 v[136:139], v93 offset:10240
	ds_read_b128 v[140:143], v93 offset:11264
	v_mfma_f32_16x16x32_bf16 v[20:23], v[96:99], v[80:83], v[20:23]
	ds_read_b128 v[96:99], v93
	v_mfma_f32_16x16x32_bf16 v[20:23], v[100:103], v[84:87], v[20:23]
	ds_read_b128 v[100:103], v93 offset:1024
	v_mfma_f32_16x16x32_bf16 v[28:31], v[104:107], v[80:83], v[28:31]
	ds_read_b128 v[104:107], v93 offset:2048
	v_mfma_f32_16x16x32_bf16 v[28:31], v[108:111], v[84:87], v[28:31]
	ds_read_b128 v[108:111], v93 offset:3072
	v_mfma_f32_16x16x32_bf16 v[24:27], v[112:115], v[80:83], v[24:27]
	ds_read_b128 v[112:115], v93 offset:4096
	v_mfma_f32_16x16x32_bf16 v[24:27], v[116:119], v[84:87], v[24:27]
	ds_read_b128 v[116:119], v93 offset:5120
	ds_read2st64_b64 v[172:175], v94 offset0:112 offset1:113
	ds_read2st64_b64 v[176:179], v94 offset0:114 offset1:115
	s_cmp_gt_u32 s3, 29
	s_cbranch_scc1 .Lscan_nodma
	s_add_i32 s0, s9, s6
	s_add_i32 m0, s0, 0x0
	s_nop 0
	global_load_lds_dwordx4 v48, s[10:11]
	s_add_i32 m0, s0, 0x2000
	s_nop 0
	global_load_lds_dwordx4 v181, s[10:11]
	s_add_i32 m0, s0, 0x4000
	s_nop 0
	global_load_lds_dwordx4 v182, s[10:11]
	s_add_i32 m0, s0, 0x6000
	s_nop 0
	global_load_lds_dwordx4 v183, s[10:11]
	s_add_i32 m0, s0, 0x8000
	s_nop 0
	global_load_lds_dwordx4 v184, s[10:11]
	s_add_i32 m0, s0, 0xa000
	s_nop 0
	global_load_lds_dwordx4 v185, s[10:11]
	s_add_i32 m0, s0, 0xc000
	s_nop 0
	global_load_lds_dwordx4 v186, s[10:11]
	s_add_i32 m0, s0, 0xe000
	s_nop 0
	global_load_lds_dwordx4 v48, s[12:13]
	s_add_i32 m0, s0, 0x10000
	s_nop 0
	global_load_lds_dwordx4 v181, s[12:13]
	s_add_u32 s10, s10, 0xe000
	s_addc_u32 s11, s11, 0
	s_add_u32 s12, s12, 0x4000
	s_addc_u32 s13, s13, 0

.LBB0_597:
	s_or_b64 exec, exec, s[36:37]
	v_readfirstlane_b32 s38, v32
	s_cmpk_gt_i32 s38, 0xff
	s_mov_b64 s[36:37], -1
	s_cbranch_scc0 .LBB0_592
	s_add_i32 s0, s16, 1
	s_cmp_gt_i32 s16, 0
	s_mov_b32 s64, 8
	s_cselect_b64 s[36:37], -1, 0
	s_mov_b32 s16, s0
	s_andn2_b64 vcc, exec, s[36:37]
	s_cbranch_vccnz .LBB0_593

.LBB0_615:
	s_add_u32 s10, s38, s16
	s_addc_u32 s11, s39, 0
	s_add_u32 s10, s10, 0x1400
	s_addc_u32 s11, s11, 0
	v_mov_b32_e32 v210, s81
	v_mad_u32_u24 v208, s80, v165, v210
	v_mad_u32_u24 v210, s80, v170, v210
	v_lshl_add_u32 v209, s80, 4, v208
	v_min_i32_e32 v208, 0x7ff, v208
	v_min_i32_e32 v209, 0x7ff, v209
	v_min_i32_e32 v210, 0x7ff, v210
	v_mad_u32_u24 v208, v208, s4, v162
	v_mad_u32_u24 v209, v209, s4, v162
	v_mad_u32_u24 v210, v210, s4, v168
	global_load_dwordx4 v[4:7], v208, s[10:11]
	global_load_dwordx4 v[0:3], v208, s[10:11] offset:64
	global_load_dwordx4 v[12:15], v209, s[10:11]
	global_load_dwordx4 v[8:11], v209, s[10:11] offset:64
	global_load_dwordx4 v[20:23], v210, s[10:11] offset:1056
	global_load_dwordx4 v[16:19], v210, s[10:11] offset:1088
	global_load_dwordx4 v[28:31], v210, s[10:11] offset:1024
	global_load_dwordx4 v[24:27], v210, s[10:11] offset:1120
	s_waitcnt vmcnt(8)
	s_branch .Latt_join

.Latt_join:
	ds_write_b128 v180, v[156:159]
	ds_write_b128 v180, v[148:151] offset:32
	ds_write_b128 v180, v[144:147] offset:64
	ds_write_b128 v180, v[152:155] offset:96
	ds_read_b64_tr_b16 v[156:157], v171
	ds_read_b64_tr_b16 v[152:153], v171 offset:32
	ds_read_b64_tr_b16 v[148:149], v171 offset:64
	ds_read_b64_tr_b16 v[144:145], v171 offset:96
	ds_read_b64_tr_b16 v[158:159], v171 offset:2304
	ds_read_b64_tr_b16 v[154:155], v171 offset:2336
	ds_read_b64_tr_b16 v[150:151], v171 offset:2368
	ds_read_b64_tr_b16 v[146:147], v171 offset:2400
	s_cmp_eq_u32 s82, 4
	s_cselect_b32 s0, 2, 0
	s_cmp_lg_u32 s82, 16
	s_cselect_b32 s43, s0, 4
	s_bitcmp0_b32 s79, 0
	s_cbranch_scc1 .LBB0_621
	v_mfma_f32_16x16x32_bf16 v[196:199], v[140:143], v[96:99], 0
	v_subrev_u32_e32 v169, s78, v166
	v_ashrrev_i32_e32 v169, s43, v169
	v_sub_u32_e32 v195, v169, v160
	v_mfma_f32_16x16x32_bf16 v[196:199], v[132:135], v[100:103], v[196:199]
	v_sub_u32_e32 v204, v160, v169
	v_cmp_gt_u32_e32 vcc, s57, v195
	v_mfma_f32_16x16x32_bf16 v[200:203], v[136:139], v[96:99], 0
	v_mfma_f32_16x16x32_bf16 v[200:203], v[128:131], v[100:103], v[200:203]
	s_nop 3
	v_mul_f32_e32 v196, 0x3e38aa3b, v196
	v_mul_f32_e32 v197, 0x3e38aa3b, v197
	v_cndmask_b32_e32 v195, v181, v196, vcc
	v_cmp_lt_u32_e32 vcc, s59, v204
	v_sub_u32_e32 v204, v169, v174
	v_mul_f32_e32 v198, 0x3e38aa3b, v198
	v_cndmask_b32_e32 v196, v181, v197, vcc
	v_cmp_gt_u32_e32 vcc, s57, v204
	v_sub_u32_e32 v204, v169, v175
	v_mul_f32_e32 v199, 0x3e38aa3b, v199
	v_cndmask_b32_e32 v198, v181, v198, vcc
	v_cmp_gt_u32_e32 vcc, s57, v204
	v_sub_u32_e32 v204, v169, v176
	v_mul_f32_e32 v200, 0x3e38aa3b, v200
	v_cndmask_b32_e32 v199, v181, v199, vcc
	v_cmp_gt_u32_e32 vcc, s57, v204
	v_sub_u32_e32 v204, v169, v177
	v_mul_f32_e32 v201, 0x3e38aa3b, v201
	v_cndmask_b32_e32 v200, v181, v200, vcc
	v_cmp_gt_u32_e32 vcc, s57, v204
	v_sub_u32_e32 v204, v169, v178
	v_max3_f32 v197, v195, s58, v196
	v_cndmask_b32_e32 v201, v181, v201, vcc
	v_mul_f32_e32 v202, 0x3e38aa3b, v202
	v_cmp_gt_u32_e32 vcc, s57, v204
	v_sub_u32_e32 v169, v169, v179
	v_max3_f32 v197, v197, v198, v199
	v_cndmask_b32_e32 v202, v181, v202, vcc
	v_mul_f32_e32 v203, 0x3e38aa3b, v203
	v_cmp_gt_u32_e32 vcc, s57, v169
	v_max3_f32 v197, v197, v200, v201
	s_nop 0
	v_cndmask_b32_e32 v169, v181, v203, vcc
	v_max3_f32 v197, v197, v202, v169
	v_mov_b32_e32 v203, v197
	s_nop 1
	v_permlane16_swap_b32_e32 v197, v203
	v_max_f32_e32 v203, v203, v203
	v_max_f32_e32 v197, v197, v197
	v_max_f32_e32 v197, v197, v203
	v_mov_b32_e32 v203, v197
	s_nop 1
	v_permlane32_swap_b32_e32 v197, v203
	v_max3_f32 v203, v191, v197, v203
	v_sub_f32_e32 v195, v195, v203
	v_exp_f32_e32 v195, v195
	v_sub_f32_e32 v196, v196, v203
	v_exp_f32_e32 v204, v196
	v_sub_f32_e32 v196, v198, v203
	v_exp_f32_e32 v205, v196
	v_sub_f32_e32 v196, v199, v203
	v_sub_f32_e32 v191, v191, v203
	v_exp_f32_e32 v206, v196
	v_sub_f32_e32 v196, v200, v203
	v_exp_f32_e32 v207, v196
	v_sub_f32_e32 v196, v201, v203
	v_exp_f32_e32 v200, v191
	v_add_f32_e32 v191, 0, v195
	v_exp_f32_e32 v201, v196
	v_sub_f32_e32 v196, v202, v203
	v_add_f32_e32 v191, v204, v191
	v_exp_f32_e32 v202, v196
	v_sub_f32_e32 v169, v169, v203
	v_add_f32_e32 v191, v205, v191
	v_exp_f32_e32 v169, v169
	v_add_f32_e32 v191, v206, v191
	v_add_f32_e32 v191, v207, v191
	v_pk_mul_f32 v[94:95], v[94:95], v[200:201] op_sel_hi:[1,0]
	v_pk_mul_f32 v[92:93], v[92:93], v[200:201] op_sel_hi:[1,0]
	v_pk_mul_f32 v[90:91], v[90:91], v[200:201] op_sel_hi:[1,0]
	v_pk_mul_f32 v[88:89], v[88:89], v[200:201] op_sel_hi:[1,0]
	v_pk_mul_f32 v[86:87], v[86:87], v[200:201] op_sel_hi:[1,0]
	v_pk_mul_f32 v[84:85], v[84:85], v[200:201] op_sel_hi:[1,0]
	v_pk_mul_f32 v[82:83], v[82:83], v[200:201] op_sel_hi:[1,0]
	v_pk_mul_f32 v[80:81], v[80:81], v[200:201] op_sel_hi:[1,0]
	v_add_f32_e32 v191, v201, v191
	v_cvt_pk_bf16_f32 v196, v195, v204
	v_cvt_pk_bf16_f32 v197, v205, v206
	v_cvt_pk_bf16_f32 v198, v207, v201
	v_cvt_pk_bf16_f32 v199, v202, v169
	v_add_f32_e32 v191, v202, v191
	s_waitcnt lgkmcnt(3)
	v_mfma_f32_16x16x32_bf16 v[92:95], v[156:159], v[196:199], v[92:95]
	v_add_f32_e32 v169, v169, v191
	v_fmac_f32_e32 v169, v186, v200
	v_mov_b32_e32 v186, v169
	s_waitcnt lgkmcnt(2)
	v_mfma_f32_16x16x32_bf16 v[88:91], v[152:155], v[196:199], v[88:91]
	v_mov_b32_e32 v191, v203
	s_waitcnt lgkmcnt(1)
	v_mfma_f32_16x16x32_bf16 v[84:87], v[148:151], v[196:199], v[84:87]
	s_waitcnt lgkmcnt(0)
	v_mfma_f32_16x16x32_bf16 v[80:83], v[144:147], v[196:199], v[80:83]
	s_bitcmp0_b32 s79, 1
	s_cbranch_scc0 .LBB0_622

.LBB0_625:
	s_waitcnt vmcnt(0)
	s_waitcnt lgkmcnt(2)
	v_mov_b64_e32 v[154:155], v[26:27]
	s_waitcnt lgkmcnt(0)
	v_mov_b64_e32 v[146:147], v[18:19]
	v_mov_b64_e32 v[150:151], v[22:23]
	v_mov_b64_e32 v[158:159], v[30:31]
	v_mov_b64_e32 v[130:131], v[10:11]
	v_mov_b64_e32 v[152:153], v[24:25]
	v_mov_b64_e32 v[144:145], v[16:17]
	v_mov_b64_e32 v[148:149], v[20:21]
	v_mov_b64_e32 v[156:157], v[28:29]
	s_mov_b32 s78, s81
	s_mov_b32 s82, s80
	s_mov_b32 s79, s42
	v_mov_b64_e32 v[128:129], v[8:9]
	v_mov_b32_e32 v140, v4
	v_mov_b32_e32 v141, v5
	v_mov_b32_e32 v142, v6
	v_mov_b32_e32 v143, v7
	v_mov_b32_e32 v132, v0
	v_mov_b32_e32 v133, v1
	v_mov_b32_e32 v134, v2
	v_mov_b32_e32 v135, v3
	v_mov_b32_e32 v136, v12
	v_mov_b32_e32 v137, v13
	v_mov_b32_e32 v138, v14
	v_mov_b32_e32 v139, v15
	s_branch .LBB0_608
